# GEMM MFMA blocks reordered accumulator-stationary: each accumulator's k=0 and k=1 MFMAs issue back to back (D->C forwarding), result order per accumulator unchanged
# speedup vs baseline: 1.0081x; 1.0058x over previous
.LBB0_101:
	ds_read_b128 v[154:157], v151
	ds_read_b128 v[158:161], v151 offset:1024
	ds_read_b128 v[162:165], v151 offset:2048
	ds_read_b128 v[166:169], v151 offset:3072
	ds_read_b128 v[170:173], v152
	ds_read_b128 v[174:177], v152 offset:1024
	ds_read_b128 v[188:191], v152 offset:2048
	ds_read_b128 v[192:195], v152 offset:3072
	s_add_u32 s40, s36, s38
	s_addc_u32 s41, s37, s39
	s_add_u32 s44, s40, 0x100
	s_addc_u32 s45, s41, 0
	s_add_u32 s42, s66, s38
	s_addc_u32 s43, s67, s39
	s_add_u32 s40, s40, 0x180
	s_addc_u32 s41, s41, 0
	s_cmpk_eq_i32 s38, 0x1f00
	s_cselect_b32 s41, s65, s41
	s_cselect_b32 s40, s64, s40
	s_cselect_b32 s43, s35, s43
	s_cselect_b32 s42, s34, s42
	s_cselect_b32 s45, s23, s45
	s_cselect_b32 s44, s22, s44
	s_mov_b32 m0, s57
	v_lshl_add_u64 v[178:179], v[146:147], 0, s[38:39]
	ds_read_b128 v[196:199], v153
	ds_read_b128 v[200:203], v153 offset:1024
	ds_read_b128 v[204:207], v153 offset:2048
	ds_read_b128 v[208:211], v153 offset:3072
	ds_read_b128 v[214:217], v153 offset:4096
	ds_read_b128 v[218:221], v153 offset:5120
	ds_read_b128 v[222:225], v153 offset:6144
	ds_read_b128 v[226:229], v153 offset:7168
	global_load_lds_dwordx4 v[178:179], off
	v_lshl_add_u64 v[178:179], v[148:149], 0, s[38:39]
	s_add_i32 m0, s47, 0xe000
	s_nop 0
	global_load_lds_dwordx4 v[178:179], off
	s_waitcnt vmcnt(8)
	s_waitcnt lgkmcnt(0)
	s_barrier
	s_setprio 1
	s_waitcnt lgkmcnt(0)
	v_mfma_f32_16x16x32_bf16 v[126:129], v[154:157], v[196:199], v[126:129]
	v_mfma_f32_16x16x32_bf16 v[126:129], v[158:161], v[200:203], v[126:129]
	v_mfma_f32_16x16x32_bf16 v[122:125], v[162:165], v[196:199], v[122:125]
	v_mfma_f32_16x16x32_bf16 v[122:125], v[166:169], v[200:203], v[122:125]
	v_mfma_f32_16x16x32_bf16 v[118:121], v[154:157], v[204:207], v[118:121]
	v_mfma_f32_16x16x32_bf16 v[118:121], v[158:161], v[208:211], v[118:121]
	v_mfma_f32_16x16x32_bf16 v[110:113], v[162:165], v[204:207], v[110:113]
	v_mfma_f32_16x16x32_bf16 v[110:113], v[166:169], v[208:211], v[110:113]
	v_mfma_f32_16x16x32_bf16 v[102:105], v[154:157], v[214:217], v[102:105]
	v_mfma_f32_16x16x32_bf16 v[102:105], v[158:161], v[218:221], v[102:105]
	v_mfma_f32_16x16x32_bf16 v[94:97], v[162:165], v[214:217], v[94:97]
	v_mfma_f32_16x16x32_bf16 v[94:97], v[166:169], v[218:221], v[94:97]
	v_mfma_f32_16x16x32_bf16 v[86:89], v[154:157], v[222:225], v[86:89]
	v_mfma_f32_16x16x32_bf16 v[86:89], v[158:161], v[226:229], v[86:89]
	v_mfma_f32_16x16x32_bf16 v[78:81], v[162:165], v[222:225], v[78:81]
	v_mfma_f32_16x16x32_bf16 v[78:81], v[166:169], v[226:229], v[78:81]
	s_setprio 0
	s_setprio 1
	v_mfma_f32_16x16x32_bf16 v[114:117], v[170:173], v[196:199], v[114:117]
	v_mfma_f32_16x16x32_bf16 v[114:117], v[174:177], v[200:203], v[114:117]
	v_mfma_f32_16x16x32_bf16 v[106:109], v[188:191], v[196:199], v[106:109]
	v_mfma_f32_16x16x32_bf16 v[106:109], v[192:195], v[200:203], v[106:109]
	v_mfma_f32_16x16x32_bf16 v[98:101], v[170:173], v[204:207], v[98:101]
	v_mfma_f32_16x16x32_bf16 v[98:101], v[174:177], v[208:211], v[98:101]
	v_mfma_f32_16x16x32_bf16 v[90:93], v[188:191], v[204:207], v[90:93]
	v_mfma_f32_16x16x32_bf16 v[90:93], v[192:195], v[208:211], v[90:93]
	v_mfma_f32_16x16x32_bf16 v[82:85], v[170:173], v[214:217], v[82:85]
	v_mfma_f32_16x16x32_bf16 v[82:85], v[174:177], v[218:221], v[82:85]
	v_mfma_f32_16x16x32_bf16 v[74:77], v[188:191], v[214:217], v[74:77]
	v_mfma_f32_16x16x32_bf16 v[74:77], v[192:195], v[218:221], v[74:77]
	v_mfma_f32_16x16x32_bf16 v[70:73], v[170:173], v[222:225], v[70:73]
	v_mfma_f32_16x16x32_bf16 v[70:73], v[174:177], v[226:229], v[70:73]
	v_mfma_f32_16x16x32_bf16 v[66:69], v[188:191], v[222:225], v[66:69]
	v_mfma_f32_16x16x32_bf16 v[66:69], v[192:195], v[226:229], v[66:69]
	s_setprio 0
	s_barrier
	s_add_i32 s69, s54, s3
	v_lshl_add_u64 v[178:179], s[42:43], 0, v[136:137]
	s_mov_b32 m0, s69
	ds_read_b128 v[196:199], v153 offset:16384
	ds_read_b128 v[200:203], v153 offset:17408
	ds_read_b128 v[204:207], v153 offset:18432
	ds_read_b128 v[208:211], v153 offset:19456
	ds_read_b128 v[214:217], v153 offset:20480
	ds_read_b128 v[218:221], v153 offset:21504
	ds_read_b128 v[222:225], v153 offset:22528
	ds_read_b128 v[226:229], v153 offset:23552
	global_load_lds_dwordx4 v[178:179], off
	s_add_i32 m0, s69, 0x2000
	s_add_u32 s70, s42, 0x108000
	v_lshl_add_u64 v[230:231], s[42:43], 0, v[140:141]
	s_addc_u32 s71, s43, 0
	s_add_i32 s69, s55, s3
	global_load_lds_dwordx4 v[230:231], off
	v_lshl_add_u64 v[232:233], s[70:71], 0, v[136:137]
	s_mov_b32 m0, s69
	s_nop 0
	global_load_lds_dwordx4 v[232:233], off
	v_lshl_add_u64 v[232:233], s[70:71], 0, v[140:141]
	s_add_i32 m0, s69, 0x2000
	s_nop 0
	global_load_lds_dwordx4 v[232:233], off
	v_lshl_add_u64 v[232:233], s[44:45], 0, v[134:135]
	s_mov_b32 m0, s47
	s_nop 0
	global_load_lds_dwordx4 v[232:233], off
	v_lshl_add_u64 v[232:233], s[44:45], 0, v[138:139]
	s_mov_b32 m0, s48
	s_nop 0
	global_load_lds_dwordx4 v[232:233], off
	s_waitcnt vmcnt(8)
	s_waitcnt lgkmcnt(0)
	s_barrier
	s_setprio 1
	s_waitcnt lgkmcnt(0)
	v_mfma_f32_16x16x32_bf16 v[62:65], v[154:157], v[196:199], v[62:65]
	v_mfma_f32_16x16x32_bf16 v[62:65], v[158:161], v[200:203], v[62:65]
	v_mfma_f32_16x16x32_bf16 v[58:61], v[162:165], v[196:199], v[58:61]
	v_mfma_f32_16x16x32_bf16 v[58:61], v[166:169], v[200:203], v[58:61]
	v_mfma_f32_16x16x32_bf16 v[54:57], v[154:157], v[204:207], v[54:57]
	v_mfma_f32_16x16x32_bf16 v[54:57], v[158:161], v[208:211], v[54:57]
	v_mfma_f32_16x16x32_bf16 v[46:49], v[162:165], v[204:207], v[46:49]
	v_mfma_f32_16x16x32_bf16 v[46:49], v[166:169], v[208:211], v[46:49]
	v_mfma_f32_16x16x32_bf16 v[38:41], v[154:157], v[214:217], v[38:41]
	v_mfma_f32_16x16x32_bf16 v[38:41], v[158:161], v[218:221], v[38:41]
	v_mfma_f32_16x16x32_bf16 v[30:33], v[162:165], v[214:217], v[30:33]
	v_mfma_f32_16x16x32_bf16 v[30:33], v[166:169], v[218:221], v[30:33]
	v_mfma_f32_16x16x32_bf16 v[22:25], v[154:157], v[222:225], v[22:25]
	v_mfma_f32_16x16x32_bf16 v[22:25], v[158:161], v[226:229], v[22:25]
	v_mfma_f32_16x16x32_bf16 v[14:17], v[162:165], v[222:225], v[14:17]
	v_mfma_f32_16x16x32_bf16 v[14:17], v[166:169], v[226:229], v[14:17]
	s_setprio 0
	s_setprio 1
	v_mfma_f32_16x16x32_bf16 v[50:53], v[170:173], v[196:199], v[50:53]
	v_mfma_f32_16x16x32_bf16 v[50:53], v[174:177], v[200:203], v[50:53]
	v_mfma_f32_16x16x32_bf16 v[42:45], v[188:191], v[196:199], v[42:45]
	v_mfma_f32_16x16x32_bf16 v[42:45], v[192:195], v[200:203], v[42:45]
	v_mfma_f32_16x16x32_bf16 v[34:37], v[170:173], v[204:207], v[34:37]
	v_mfma_f32_16x16x32_bf16 v[34:37], v[174:177], v[208:211], v[34:37]
	v_mfma_f32_16x16x32_bf16 v[26:29], v[188:191], v[204:207], v[26:29]
	v_mfma_f32_16x16x32_bf16 v[26:29], v[192:195], v[208:211], v[26:29]
	v_mfma_f32_16x16x32_bf16 v[18:21], v[170:173], v[214:217], v[18:21]
	v_mfma_f32_16x16x32_bf16 v[18:21], v[174:177], v[218:221], v[18:21]
	v_mfma_f32_16x16x32_bf16 v[10:13], v[188:191], v[214:217], v[10:13]
	v_mfma_f32_16x16x32_bf16 v[10:13], v[192:195], v[218:221], v[10:13]
	v_mfma_f32_16x16x32_bf16 v[6:9], v[170:173], v[222:225], v[6:9]
	v_mfma_f32_16x16x32_bf16 v[6:9], v[174:177], v[226:229], v[6:9]
	v_mfma_f32_16x16x32_bf16 v[2:5], v[188:191], v[222:225], v[2:5]
	v_mfma_f32_16x16x32_bf16 v[2:5], v[192:195], v[226:229], v[2:5]
	s_setprio 0
	s_barrier
	s_add_i32 s69, 0, 0x18000
	s_add_i32 s70, 0, 0x1c000
	v_add_u32_e32 v166, s69, v133
	v_add_u32_e32 v187, s70, v133
	ds_read_b128 v[154:157], v166
	ds_read_b128 v[158:161], v166 offset:1024
	ds_read_b128 v[162:165], v166 offset:2048
	ds_read_b128 v[166:169], v166 offset:3072
	ds_read_b128 v[170:173], v187
	ds_read_b128 v[174:177], v187 offset:1024
	ds_read_b128 v[188:191], v187 offset:2048
	ds_read_b128 v[192:195], v187 offset:3072
	s_add_u32 s44, s44, 0x108000
	s_addc_u32 s45, s45, 0
	s_mov_b32 m0, s49
	v_lshl_add_u64 v[232:233], s[44:45], 0, v[134:135]
	ds_read_b128 v[196:199], v153 offset:32768
	ds_read_b128 v[200:203], v153 offset:33792
	ds_read_b128 v[204:207], v153 offset:34816
	ds_read_b128 v[208:211], v153 offset:35840
	ds_read_b128 v[214:217], v153 offset:36864
	ds_read_b128 v[218:221], v153 offset:37888
	ds_read_b128 v[222:225], v153 offset:38912
	ds_read_b128 v[226:229], v153 offset:39936
	global_load_lds_dwordx4 v[232:233], off
	v_lshl_add_u64 v[232:233], s[44:45], 0, v[138:139]
	s_mov_b32 m0, s50
	s_nop 0
	global_load_lds_dwordx4 v[232:233], off
	s_waitcnt vmcnt(8)
	s_waitcnt lgkmcnt(0)
	s_barrier
	s_setprio 1
	s_waitcnt lgkmcnt(0)
	v_mfma_f32_16x16x32_bf16 v[126:129], v[154:157], v[196:199], v[126:129]
	v_mfma_f32_16x16x32_bf16 v[126:129], v[158:161], v[200:203], v[126:129]
	v_mfma_f32_16x16x32_bf16 v[122:125], v[162:165], v[196:199], v[122:125]
	v_mfma_f32_16x16x32_bf16 v[122:125], v[166:169], v[200:203], v[122:125]
	v_mfma_f32_16x16x32_bf16 v[118:121], v[154:157], v[204:207], v[118:121]
	v_mfma_f32_16x16x32_bf16 v[118:121], v[158:161], v[208:211], v[118:121]
	v_mfma_f32_16x16x32_bf16 v[110:113], v[162:165], v[204:207], v[110:113]
	v_mfma_f32_16x16x32_bf16 v[110:113], v[166:169], v[208:211], v[110:113]
	v_mfma_f32_16x16x32_bf16 v[102:105], v[154:157], v[214:217], v[102:105]
	v_mfma_f32_16x16x32_bf16 v[102:105], v[158:161], v[218:221], v[102:105]
	v_mfma_f32_16x16x32_bf16 v[94:97], v[162:165], v[214:217], v[94:97]
	v_mfma_f32_16x16x32_bf16 v[94:97], v[166:169], v[218:221], v[94:97]
	v_mfma_f32_16x16x32_bf16 v[86:89], v[154:157], v[222:225], v[86:89]
	v_mfma_f32_16x16x32_bf16 v[86:89], v[158:161], v[226:229], v[86:89]
	v_mfma_f32_16x16x32_bf16 v[78:81], v[162:165], v[222:225], v[78:81]
	v_mfma_f32_16x16x32_bf16 v[78:81], v[166:169], v[226:229], v[78:81]
	s_setprio 0
	s_setprio 1
	v_mfma_f32_16x16x32_bf16 v[114:117], v[170:173], v[196:199], v[114:117]
	v_mfma_f32_16x16x32_bf16 v[114:117], v[174:177], v[200:203], v[114:117]
	v_mfma_f32_16x16x32_bf16 v[106:109], v[188:191], v[196:199], v[106:109]
	v_mfma_f32_16x16x32_bf16 v[106:109], v[192:195], v[200:203], v[106:109]
	v_mfma_f32_16x16x32_bf16 v[98:101], v[170:173], v[204:207], v[98:101]
	v_mfma_f32_16x16x32_bf16 v[98:101], v[174:177], v[208:211], v[98:101]
	v_mfma_f32_16x16x32_bf16 v[90:93], v[188:191], v[204:207], v[90:93]
	v_mfma_f32_16x16x32_bf16 v[90:93], v[192:195], v[208:211], v[90:93]
	v_mfma_f32_16x16x32_bf16 v[82:85], v[170:173], v[214:217], v[82:85]
	v_mfma_f32_16x16x32_bf16 v[82:85], v[174:177], v[218:221], v[82:85]
	v_mfma_f32_16x16x32_bf16 v[74:77], v[188:191], v[214:217], v[74:77]
	v_mfma_f32_16x16x32_bf16 v[74:77], v[192:195], v[218:221], v[74:77]
	v_mfma_f32_16x16x32_bf16 v[70:73], v[170:173], v[222:225], v[70:73]
	v_mfma_f32_16x16x32_bf16 v[70:73], v[174:177], v[226:229], v[70:73]
	v_mfma_f32_16x16x32_bf16 v[66:69], v[188:191], v[222:225], v[66:69]
	v_mfma_f32_16x16x32_bf16 v[66:69], v[192:195], v[226:229], v[66:69]
	s_setprio 0
	s_barrier
	s_add_i32 s44, s69, s3
	v_lshl_add_u64 v[178:179], v[178:179], 0, s[12:13]
	s_mov_b32 m0, s44
	ds_read_b128 v[196:199], v153 offset:49152
	ds_read_b128 v[200:203], v153 offset:50176
	ds_read_b128 v[204:207], v153 offset:51200
	ds_read_b128 v[208:211], v153 offset:52224
	ds_read_b128 v[214:217], v153 offset:53248
	ds_read_b128 v[218:221], v153 offset:54272
	ds_read_b128 v[222:225], v153 offset:55296
	ds_read_b128 v[226:229], v153 offset:56320
	global_load_lds_dwordx4 v[178:179], off
	s_add_i32 m0, s44, 0x2000
	s_add_u32 s42, s42, 0x108080
	v_lshl_add_u64 v[178:179], v[230:231], 0, s[12:13]
	s_addc_u32 s43, s43, 0
	s_add_i32 s44, s70, s3
	global_load_lds_dwordx4 v[178:179], off
	v_lshl_add_u64 v[178:179], s[42:43], 0, v[136:137]
	s_mov_b32 m0, s44
	s_nop 0
	global_load_lds_dwordx4 v[178:179], off
	v_lshl_add_u64 v[178:179], s[42:43], 0, v[140:141]
	s_add_i32 m0, s44, 0x2000
	s_nop 0
	global_load_lds_dwordx4 v[178:179], off
	v_lshl_add_u64 v[178:179], s[40:41], 0, v[134:135]
	s_mov_b32 m0, s52
	s_nop 0
	global_load_lds_dwordx4 v[178:179], off
	v_lshl_add_u64 v[178:179], s[40:41], 0, v[138:139]
	s_mov_b32 m0, s53
	s_nop 0
	global_load_lds_dwordx4 v[178:179], off
	s_waitcnt vmcnt(8)
	s_waitcnt lgkmcnt(0)
	s_barrier
	s_setprio 1
	s_waitcnt lgkmcnt(0)
	v_mfma_f32_16x16x32_bf16 v[62:65], v[154:157], v[196:199], v[62:65]
	v_mfma_f32_16x16x32_bf16 v[62:65], v[158:161], v[200:203], v[62:65]
	v_mfma_f32_16x16x32_bf16 v[58:61], v[162:165], v[196:199], v[58:61]
	v_mfma_f32_16x16x32_bf16 v[58:61], v[166:169], v[200:203], v[58:61]
	v_mfma_f32_16x16x32_bf16 v[54:57], v[154:157], v[204:207], v[54:57]
	v_mfma_f32_16x16x32_bf16 v[54:57], v[158:161], v[208:211], v[54:57]
	v_mfma_f32_16x16x32_bf16 v[46:49], v[162:165], v[204:207], v[46:49]
	v_mfma_f32_16x16x32_bf16 v[46:49], v[166:169], v[208:211], v[46:49]
	v_mfma_f32_16x16x32_bf16 v[38:41], v[154:157], v[214:217], v[38:41]
	v_mfma_f32_16x16x32_bf16 v[38:41], v[158:161], v[218:221], v[38:41]
	v_mfma_f32_16x16x32_bf16 v[30:33], v[162:165], v[214:217], v[30:33]
	v_mfma_f32_16x16x32_bf16 v[30:33], v[166:169], v[218:221], v[30:33]
	v_mfma_f32_16x16x32_bf16 v[22:25], v[154:157], v[222:225], v[22:25]
	v_mfma_f32_16x16x32_bf16 v[22:25], v[158:161], v[226:229], v[22:25]
	v_mfma_f32_16x16x32_bf16 v[14:17], v[162:165], v[222:225], v[14:17]
	v_mfma_f32_16x16x32_bf16 v[14:17], v[166:169], v[226:229], v[14:17]
	s_setprio 0
	s_setprio 1
	v_mfma_f32_16x16x32_bf16 v[50:53], v[170:173], v[196:199], v[50:53]
	v_mfma_f32_16x16x32_bf16 v[50:53], v[174:177], v[200:203], v[50:53]
	v_mfma_f32_16x16x32_bf16 v[42:45], v[188:191], v[196:199], v[42:45]
	v_mfma_f32_16x16x32_bf16 v[42:45], v[192:195], v[200:203], v[42:45]
	v_mfma_f32_16x16x32_bf16 v[34:37], v[170:173], v[204:207], v[34:37]
	v_mfma_f32_16x16x32_bf16 v[34:37], v[174:177], v[208:211], v[34:37]
	v_mfma_f32_16x16x32_bf16 v[26:29], v[188:191], v[204:207], v[26:29]
	v_mfma_f32_16x16x32_bf16 v[26:29], v[192:195], v[208:211], v[26:29]
	v_mfma_f32_16x16x32_bf16 v[18:21], v[170:173], v[214:217], v[18:21]
	v_mfma_f32_16x16x32_bf16 v[18:21], v[174:177], v[218:221], v[18:21]
	v_mfma_f32_16x16x32_bf16 v[10:13], v[188:191], v[214:217], v[10:13]
	v_mfma_f32_16x16x32_bf16 v[10:13], v[192:195], v[218:221], v[10:13]
	v_mfma_f32_16x16x32_bf16 v[6:9], v[170:173], v[222:225], v[6:9]
	v_mfma_f32_16x16x32_bf16 v[6:9], v[174:177], v[226:229], v[6:9]
	v_mfma_f32_16x16x32_bf16 v[2:5], v[188:191], v[222:225], v[2:5]
	v_mfma_f32_16x16x32_bf16 v[2:5], v[192:195], v[226:229], v[2:5]
	s_setprio 0
	s_barrier
	s_add_i32 s68, s68, 2
	s_add_u32 s38, s38, 0x100
	s_addc_u32 s39, s39, 0
	s_cmp_gt_u32 s68, 61
	s_cbranch_scc0 .LBB0_101
	s_and_b64 vcc, exec, s[20:21]
	s_cbranch_vccz .LBB0_104
	s_barrier

.LBB0_235:
	ds_read_b128 v[156:159], v150
	ds_read_b128 v[160:163], v150 offset:1024
	ds_read_b128 v[164:167], v150 offset:2048
	ds_read_b128 v[168:171], v150 offset:3072
	ds_read_b128 v[172:175], v151
	ds_read_b128 v[176:179], v151 offset:1024
	ds_read_b128 v[180:183], v151 offset:2048
	ds_read_b128 v[184:187], v151 offset:3072
	s_add_u32 s36, s4, s34
	s_addc_u32 s37, s5, s35
	s_add_u32 s40, s36, 0x100
	s_addc_u32 s41, s37, 0
	s_add_u32 s38, s62, s34
	s_addc_u32 s39, s63, s35
	s_add_u32 s36, s36, 0x180
	s_addc_u32 s37, s37, 0
	s_cmpk_eq_i32 s34, 0x1f00
	s_cselect_b32 s37, s61, s37
	s_cselect_b32 s36, s60, s36
	s_cselect_b32 s39, s31, s39
	s_cselect_b32 s38, s30, s38
	s_cselect_b32 s41, s23, s41
	s_cselect_b32 s40, s22, s40
	s_mov_b32 m0, s46
	v_lshl_add_u64 v[222:223], v[146:147], 0, s[34:35]
	ds_read_b128 v[188:191], v152
	ds_read_b128 v[192:195], v152 offset:1024
	ds_read_b128 v[196:199], v152 offset:2048
	ds_read_b128 v[200:203], v152 offset:3072
	ds_read_b128 v[204:207], v152 offset:4096
	ds_read_b128 v[208:211], v152 offset:5120
	ds_read_b128 v[214:217], v152 offset:6144
	ds_read_b128 v[218:221], v152 offset:7168
	global_load_lds_dwordx4 v[222:223], off
	v_lshl_add_u64 v[222:223], v[148:149], 0, s[34:35]
	s_mov_b32 m0, s47
	s_nop 0
	global_load_lds_dwordx4 v[222:223], off
	s_waitcnt vmcnt(8)
	s_waitcnt lgkmcnt(0)
	s_barrier
	s_setprio 1
	s_waitcnt lgkmcnt(0)
	v_mfma_f32_16x16x32_bf16 v[126:129], v[156:159], v[188:191], v[126:129]
	v_mfma_f32_16x16x32_bf16 v[126:129], v[160:163], v[192:195], v[126:129]
	v_mfma_f32_16x16x32_bf16 v[122:125], v[164:167], v[188:191], v[122:125]
	v_mfma_f32_16x16x32_bf16 v[122:125], v[168:171], v[192:195], v[122:125]
	v_mfma_f32_16x16x32_bf16 v[110:113], v[156:159], v[196:199], v[110:113]
	v_mfma_f32_16x16x32_bf16 v[110:113], v[160:163], v[200:203], v[110:113]
	v_mfma_f32_16x16x32_bf16 v[106:109], v[164:167], v[196:199], v[106:109]
	v_mfma_f32_16x16x32_bf16 v[106:109], v[168:171], v[200:203], v[106:109]
	v_mfma_f32_16x16x32_bf16 v[94:97], v[156:159], v[204:207], v[94:97]
	v_mfma_f32_16x16x32_bf16 v[94:97], v[160:163], v[208:211], v[94:97]
	v_mfma_f32_16x16x32_bf16 v[90:93], v[164:167], v[204:207], v[90:93]
	v_mfma_f32_16x16x32_bf16 v[90:93], v[168:171], v[208:211], v[90:93]
	v_mfma_f32_16x16x32_bf16 v[78:81], v[156:159], v[214:217], v[78:81]
	v_mfma_f32_16x16x32_bf16 v[78:81], v[160:163], v[218:221], v[78:81]
	v_mfma_f32_16x16x32_bf16 v[74:77], v[164:167], v[214:217], v[74:77]
	v_mfma_f32_16x16x32_bf16 v[74:77], v[168:171], v[218:221], v[74:77]
	s_setprio 0
	s_setprio 1
	v_mfma_f32_16x16x32_bf16 v[118:121], v[172:175], v[188:191], v[118:121]
	v_mfma_f32_16x16x32_bf16 v[118:121], v[176:179], v[192:195], v[118:121]
	v_mfma_f32_16x16x32_bf16 v[114:117], v[180:183], v[188:191], v[114:117]
	v_mfma_f32_16x16x32_bf16 v[114:117], v[184:187], v[192:195], v[114:117]
	v_mfma_f32_16x16x32_bf16 v[102:105], v[172:175], v[196:199], v[102:105]
	v_mfma_f32_16x16x32_bf16 v[102:105], v[176:179], v[200:203], v[102:105]
	v_mfma_f32_16x16x32_bf16 v[98:101], v[180:183], v[196:199], v[98:101]
	v_mfma_f32_16x16x32_bf16 v[98:101], v[184:187], v[200:203], v[98:101]
	v_mfma_f32_16x16x32_bf16 v[86:89], v[172:175], v[204:207], v[86:89]
	v_mfma_f32_16x16x32_bf16 v[86:89], v[176:179], v[208:211], v[86:89]
	v_mfma_f32_16x16x32_bf16 v[82:85], v[180:183], v[204:207], v[82:85]
	v_mfma_f32_16x16x32_bf16 v[82:85], v[184:187], v[208:211], v[82:85]
	v_mfma_f32_16x16x32_bf16 v[70:73], v[172:175], v[214:217], v[70:73]
	v_mfma_f32_16x16x32_bf16 v[70:73], v[176:179], v[218:221], v[70:73]
	v_mfma_f32_16x16x32_bf16 v[66:69], v[180:183], v[214:217], v[66:69]
	v_mfma_f32_16x16x32_bf16 v[66:69], v[184:187], v[218:221], v[66:69]
	s_setprio 0
	s_barrier
	s_mov_b32 m0, s48
	v_lshl_add_u64 v[222:223], s[38:39], 0, v[132:133]
	s_add_u32 s66, s38, 0x108000
	ds_read_b128 v[188:191], v152 offset:16384
	ds_read_b128 v[192:195], v152 offset:17408
	ds_read_b128 v[196:199], v152 offset:18432
	ds_read_b128 v[200:203], v152 offset:19456
	ds_read_b128 v[204:207], v152 offset:20480
	ds_read_b128 v[208:211], v152 offset:21504
	ds_read_b128 v[214:217], v152 offset:22528
	ds_read_b128 v[218:221], v152 offset:23552
	global_load_lds_dwordx4 v[222:223], off
	v_lshl_add_u64 v[224:225], s[38:39], 0, v[136:137]
	s_mov_b32 m0, s49
	s_addc_u32 s67, s39, 0
	global_load_lds_dwordx4 v[224:225], off
	v_lshl_add_u64 v[226:227], s[66:67], 0, v[132:133]
	s_mov_b32 m0, s50
	s_nop 0
	global_load_lds_dwordx4 v[226:227], off
	v_lshl_add_u64 v[226:227], s[66:67], 0, v[136:137]
	s_mov_b32 m0, s51
	s_nop 0
	global_load_lds_dwordx4 v[226:227], off
	v_lshl_add_u64 v[226:227], s[40:41], 0, v[130:131]
	s_mov_b32 m0, s3
	s_nop 0
	global_load_lds_dwordx4 v[226:227], off
	v_lshl_add_u64 v[226:227], s[40:41], 0, v[134:135]
	s_mov_b32 m0, s33
	s_nop 0
	global_load_lds_dwordx4 v[226:227], off
	s_waitcnt vmcnt(8)
	s_waitcnt lgkmcnt(0)
	s_barrier
	s_setprio 1
	s_waitcnt lgkmcnt(0)
	v_mfma_f32_16x16x32_bf16 v[62:65], v[156:159], v[188:191], v[62:65]
	v_mfma_f32_16x16x32_bf16 v[62:65], v[160:163], v[192:195], v[62:65]
	v_mfma_f32_16x16x32_bf16 v[58:61], v[164:167], v[188:191], v[58:61]
	v_mfma_f32_16x16x32_bf16 v[58:61], v[168:171], v[192:195], v[58:61]
	v_mfma_f32_16x16x32_bf16 v[46:49], v[156:159], v[196:199], v[46:49]
	v_mfma_f32_16x16x32_bf16 v[46:49], v[160:163], v[200:203], v[46:49]
	v_mfma_f32_16x16x32_bf16 v[42:45], v[164:167], v[196:199], v[42:45]
	v_mfma_f32_16x16x32_bf16 v[42:45], v[168:171], v[200:203], v[42:45]
	v_mfma_f32_16x16x32_bf16 v[30:33], v[156:159], v[204:207], v[30:33]
	v_mfma_f32_16x16x32_bf16 v[30:33], v[160:163], v[208:211], v[30:33]
	v_mfma_f32_16x16x32_bf16 v[26:29], v[164:167], v[204:207], v[26:29]
	v_mfma_f32_16x16x32_bf16 v[26:29], v[168:171], v[208:211], v[26:29]
	v_mfma_f32_16x16x32_bf16 v[14:17], v[156:159], v[214:217], v[14:17]
	v_mfma_f32_16x16x32_bf16 v[14:17], v[160:163], v[218:221], v[14:17]
	v_mfma_f32_16x16x32_bf16 v[10:13], v[164:167], v[214:217], v[10:13]
	v_mfma_f32_16x16x32_bf16 v[10:13], v[168:171], v[218:221], v[10:13]
	s_setprio 0
	s_setprio 1
	v_mfma_f32_16x16x32_bf16 v[54:57], v[172:175], v[188:191], v[54:57]
	v_mfma_f32_16x16x32_bf16 v[54:57], v[176:179], v[192:195], v[54:57]
	v_mfma_f32_16x16x32_bf16 v[50:53], v[180:183], v[188:191], v[50:53]
	v_mfma_f32_16x16x32_bf16 v[50:53], v[184:187], v[192:195], v[50:53]
	v_mfma_f32_16x16x32_bf16 v[38:41], v[172:175], v[196:199], v[38:41]
	v_mfma_f32_16x16x32_bf16 v[38:41], v[176:179], v[200:203], v[38:41]
	v_mfma_f32_16x16x32_bf16 v[34:37], v[180:183], v[196:199], v[34:37]
	v_mfma_f32_16x16x32_bf16 v[34:37], v[184:187], v[200:203], v[34:37]
	v_mfma_f32_16x16x32_bf16 v[22:25], v[172:175], v[204:207], v[22:25]
	v_mfma_f32_16x16x32_bf16 v[22:25], v[176:179], v[208:211], v[22:25]
	v_mfma_f32_16x16x32_bf16 v[18:21], v[180:183], v[204:207], v[18:21]
	v_mfma_f32_16x16x32_bf16 v[18:21], v[184:187], v[208:211], v[18:21]
	v_mfma_f32_16x16x32_bf16 v[6:9], v[172:175], v[214:217], v[6:9]
	v_mfma_f32_16x16x32_bf16 v[6:9], v[176:179], v[218:221], v[6:9]
	v_mfma_f32_16x16x32_bf16 v[2:5], v[180:183], v[214:217], v[2:5]
	v_mfma_f32_16x16x32_bf16 v[2:5], v[184:187], v[218:221], v[2:5]
	s_setprio 0
	s_barrier
	ds_read_b128 v[156:159], v153
	ds_read_b128 v[160:163], v153 offset:1024
	ds_read_b128 v[164:167], v153 offset:2048
	ds_read_b128 v[168:171], v153 offset:3072
	ds_read_b128 v[172:175], v154
	ds_read_b128 v[176:179], v154 offset:1024
	ds_read_b128 v[180:183], v154 offset:2048
	ds_read_b128 v[184:187], v154 offset:3072
	s_add_u32 s40, s40, 0x108000
	s_addc_u32 s41, s41, 0
	s_mov_b32 m0, s42
	v_lshl_add_u64 v[226:227], s[40:41], 0, v[130:131]
	ds_read_b128 v[188:191], v152 offset:32768
	ds_read_b128 v[192:195], v152 offset:33792
	ds_read_b128 v[196:199], v152 offset:34816
	ds_read_b128 v[200:203], v152 offset:35840
	ds_read_b128 v[204:207], v152 offset:36864
	ds_read_b128 v[208:211], v152 offset:37888
	ds_read_b128 v[214:217], v152 offset:38912
	ds_read_b128 v[218:221], v152 offset:39936
	global_load_lds_dwordx4 v[226:227], off
	v_lshl_add_u64 v[226:227], s[40:41], 0, v[134:135]
	s_mov_b32 m0, s43
	s_nop 0
	global_load_lds_dwordx4 v[226:227], off
	s_waitcnt vmcnt(8)
	s_waitcnt lgkmcnt(0)
	s_barrier
	s_setprio 1
	s_waitcnt lgkmcnt(0)
	v_mfma_f32_16x16x32_bf16 v[126:129], v[156:159], v[188:191], v[126:129]
	v_mfma_f32_16x16x32_bf16 v[126:129], v[160:163], v[192:195], v[126:129]
	v_mfma_f32_16x16x32_bf16 v[122:125], v[164:167], v[188:191], v[122:125]
	v_mfma_f32_16x16x32_bf16 v[122:125], v[168:171], v[192:195], v[122:125]
	v_mfma_f32_16x16x32_bf16 v[110:113], v[156:159], v[196:199], v[110:113]
	v_mfma_f32_16x16x32_bf16 v[110:113], v[160:163], v[200:203], v[110:113]
	v_mfma_f32_16x16x32_bf16 v[106:109], v[164:167], v[196:199], v[106:109]
	v_mfma_f32_16x16x32_bf16 v[106:109], v[168:171], v[200:203], v[106:109]
	v_mfma_f32_16x16x32_bf16 v[94:97], v[156:159], v[204:207], v[94:97]
	v_mfma_f32_16x16x32_bf16 v[94:97], v[160:163], v[208:211], v[94:97]
	v_mfma_f32_16x16x32_bf16 v[90:93], v[164:167], v[204:207], v[90:93]
	v_mfma_f32_16x16x32_bf16 v[90:93], v[168:171], v[208:211], v[90:93]
	v_mfma_f32_16x16x32_bf16 v[78:81], v[156:159], v[214:217], v[78:81]
	v_mfma_f32_16x16x32_bf16 v[78:81], v[160:163], v[218:221], v[78:81]
	v_mfma_f32_16x16x32_bf16 v[74:77], v[164:167], v[214:217], v[74:77]
	v_mfma_f32_16x16x32_bf16 v[74:77], v[168:171], v[218:221], v[74:77]
	s_setprio 0
	s_setprio 1
	v_mfma_f32_16x16x32_bf16 v[118:121], v[172:175], v[188:191], v[118:121]
	v_mfma_f32_16x16x32_bf16 v[118:121], v[176:179], v[192:195], v[118:121]
	v_mfma_f32_16x16x32_bf16 v[114:117], v[180:183], v[188:191], v[114:117]
	v_mfma_f32_16x16x32_bf16 v[114:117], v[184:187], v[192:195], v[114:117]
	v_mfma_f32_16x16x32_bf16 v[102:105], v[172:175], v[196:199], v[102:105]
	v_mfma_f32_16x16x32_bf16 v[102:105], v[176:179], v[200:203], v[102:105]
	v_mfma_f32_16x16x32_bf16 v[98:101], v[180:183], v[196:199], v[98:101]
	v_mfma_f32_16x16x32_bf16 v[98:101], v[184:187], v[200:203], v[98:101]
	v_mfma_f32_16x16x32_bf16 v[86:89], v[172:175], v[204:207], v[86:89]
	v_mfma_f32_16x16x32_bf16 v[86:89], v[176:179], v[208:211], v[86:89]
	v_mfma_f32_16x16x32_bf16 v[82:85], v[180:183], v[204:207], v[82:85]
	v_mfma_f32_16x16x32_bf16 v[82:85], v[184:187], v[208:211], v[82:85]
	v_mfma_f32_16x16x32_bf16 v[70:73], v[172:175], v[214:217], v[70:73]
	v_mfma_f32_16x16x32_bf16 v[70:73], v[176:179], v[218:221], v[70:73]
	v_mfma_f32_16x16x32_bf16 v[66:69], v[180:183], v[214:217], v[66:69]
	v_mfma_f32_16x16x32_bf16 v[66:69], v[184:187], v[218:221], v[66:69]
	s_setprio 0
	s_barrier
	s_mov_b32 m0, s53
	v_lshl_add_u64 v[222:223], v[222:223], 0, s[16:17]
	s_add_u32 s38, s38, 0x108080
	ds_read_b128 v[188:191], v152 offset:49152
	ds_read_b128 v[192:195], v152 offset:50176
	ds_read_b128 v[196:199], v152 offset:51200
	ds_read_b128 v[200:203], v152 offset:52224
	ds_read_b128 v[204:207], v152 offset:53248
	ds_read_b128 v[208:211], v152 offset:54272
	ds_read_b128 v[214:217], v152 offset:55296
	ds_read_b128 v[218:221], v152 offset:56320
	global_load_lds_dwordx4 v[222:223], off
	v_lshl_add_u64 v[222:223], v[224:225], 0, s[16:17]
	s_mov_b32 m0, s54
	s_addc_u32 s39, s39, 0
	s_add_i32 s40, s52, s2
	global_load_lds_dwordx4 v[222:223], off
	v_lshl_add_u64 v[222:223], s[38:39], 0, v[132:133]
	s_mov_b32 m0, s40
	s_nop 0
	global_load_lds_dwordx4 v[222:223], off
	v_lshl_add_u64 v[222:223], s[38:39], 0, v[136:137]
	s_add_i32 m0, s40, 0x2000
	s_nop 0
	global_load_lds_dwordx4 v[222:223], off
	v_lshl_add_u64 v[222:223], s[36:37], 0, v[130:131]
	s_mov_b32 m0, s44
	s_nop 0
	global_load_lds_dwordx4 v[222:223], off
	v_lshl_add_u64 v[222:223], s[36:37], 0, v[134:135]
	s_mov_b32 m0, s45
	s_nop 0
	global_load_lds_dwordx4 v[222:223], off
	s_waitcnt vmcnt(8)
	s_waitcnt lgkmcnt(0)
	s_barrier
	s_setprio 1
	s_waitcnt lgkmcnt(0)
	v_mfma_f32_16x16x32_bf16 v[62:65], v[156:159], v[188:191], v[62:65]
	v_mfma_f32_16x16x32_bf16 v[62:65], v[160:163], v[192:195], v[62:65]
	v_mfma_f32_16x16x32_bf16 v[58:61], v[164:167], v[188:191], v[58:61]
	v_mfma_f32_16x16x32_bf16 v[58:61], v[168:171], v[192:195], v[58:61]
	v_mfma_f32_16x16x32_bf16 v[46:49], v[156:159], v[196:199], v[46:49]
	v_mfma_f32_16x16x32_bf16 v[46:49], v[160:163], v[200:203], v[46:49]
	v_mfma_f32_16x16x32_bf16 v[42:45], v[164:167], v[196:199], v[42:45]
	v_mfma_f32_16x16x32_bf16 v[42:45], v[168:171], v[200:203], v[42:45]
	v_mfma_f32_16x16x32_bf16 v[30:33], v[156:159], v[204:207], v[30:33]
	v_mfma_f32_16x16x32_bf16 v[30:33], v[160:163], v[208:211], v[30:33]
	v_mfma_f32_16x16x32_bf16 v[26:29], v[164:167], v[204:207], v[26:29]
	v_mfma_f32_16x16x32_bf16 v[26:29], v[168:171], v[208:211], v[26:29]
	v_mfma_f32_16x16x32_bf16 v[14:17], v[156:159], v[214:217], v[14:17]
	v_mfma_f32_16x16x32_bf16 v[14:17], v[160:163], v[218:221], v[14:17]
	v_mfma_f32_16x16x32_bf16 v[10:13], v[164:167], v[214:217], v[10:13]
	v_mfma_f32_16x16x32_bf16 v[10:13], v[168:171], v[218:221], v[10:13]
	s_setprio 0
	s_setprio 1
	v_mfma_f32_16x16x32_bf16 v[54:57], v[172:175], v[188:191], v[54:57]
	v_mfma_f32_16x16x32_bf16 v[54:57], v[176:179], v[192:195], v[54:57]
	v_mfma_f32_16x16x32_bf16 v[50:53], v[180:183], v[188:191], v[50:53]
	v_mfma_f32_16x16x32_bf16 v[50:53], v[184:187], v[192:195], v[50:53]
	v_mfma_f32_16x16x32_bf16 v[38:41], v[172:175], v[196:199], v[38:41]
	v_mfma_f32_16x16x32_bf16 v[38:41], v[176:179], v[200:203], v[38:41]
	v_mfma_f32_16x16x32_bf16 v[34:37], v[180:183], v[196:199], v[34:37]
	v_mfma_f32_16x16x32_bf16 v[34:37], v[184:187], v[200:203], v[34:37]
	v_mfma_f32_16x16x32_bf16 v[22:25], v[172:175], v[204:207], v[22:25]
	v_mfma_f32_16x16x32_bf16 v[22:25], v[176:179], v[208:211], v[22:25]
	v_mfma_f32_16x16x32_bf16 v[18:21], v[180:183], v[204:207], v[18:21]
	v_mfma_f32_16x16x32_bf16 v[18:21], v[184:187], v[208:211], v[18:21]
	v_mfma_f32_16x16x32_bf16 v[6:9], v[172:175], v[214:217], v[6:9]
	v_mfma_f32_16x16x32_bf16 v[6:9], v[176:179], v[218:221], v[6:9]
	v_mfma_f32_16x16x32_bf16 v[2:5], v[180:183], v[214:217], v[2:5]
	v_mfma_f32_16x16x32_bf16 v[2:5], v[184:187], v[218:221], v[2:5]
	s_setprio 0
	s_barrier
	s_add_i32 s64, s64, 2
	s_add_u32 s34, s34, 0x100
	s_addc_u32 s35, s35, 0
	s_cmp_gt_u32 s64, 61
	s_cbranch_scc0 .LBB0_235
	s_and_b64 vcc, exec, s[20:21]
	s_cbranch_vccz .LBB0_238
	s_barrier

.LBB0_434:
	ds_read_b128 v[134:137], v204
	ds_read_b128 v[138:141], v204 offset:1024
	ds_read_b128 v[142:145], v204 offset:2048
	ds_read_b128 v[146:149], v204 offset:3072
	ds_read_b128 v[150:153], v205
	ds_read_b128 v[154:157], v205 offset:1024
	ds_read_b128 v[158:161], v205 offset:2048
	ds_read_b128 v[162:165], v205 offset:3072
	s_add_u32 s34, s22, s30
	s_addc_u32 s35, s23, s31
	s_add_u32 s38, s34, 0x100
	s_addc_u32 s39, s35, 0
	s_add_u32 s36, s60, s30
	s_addc_u32 s37, s61, s31
	s_add_u32 s34, s34, 0x180
	s_addc_u32 s35, s35, 0
	s_cmpk_eq_i32 s30, 0xb00
	s_cselect_b32 s35, s59, s35
	s_cselect_b32 s34, s58, s34
	s_cselect_b32 s37, s21, s37
	s_cselect_b32 s36, s20, s36
	s_cselect_b32 s39, s17, s39
	s_cselect_b32 s38, s16, s38
	v_lshl_add_u64 v[200:201], v[130:131], 0, s[30:31]
	s_add_i32 m0, s3, 0xc000
	ds_read_b128 v[166:169], v206
	ds_read_b128 v[170:173], v206 offset:1024
	ds_read_b128 v[174:177], v206 offset:2048
	ds_read_b128 v[178:181], v206 offset:3072
	ds_read_b128 v[182:185], v206 offset:4096
	ds_read_b128 v[208:211], v206 offset:5120
	ds_read_b128 v[214:217], v206 offset:6144
	ds_read_b128 v[218:221], v206 offset:7168
	global_load_lds_dwordx4 v[200:201], off
	v_lshl_add_u64 v[200:201], v[132:133], 0, s[30:31]
	s_add_i32 m0, s3, 0xe000
	s_nop 0
	global_load_lds_dwordx4 v[200:201], off
	s_waitcnt vmcnt(8)
	s_waitcnt lgkmcnt(0)
	s_barrier
	s_setprio 1
	s_waitcnt lgkmcnt(0)
	v_mfma_f32_16x16x32_bf16 v[126:129], v[134:137], v[166:169], v[126:129]
	v_mfma_f32_16x16x32_bf16 v[126:129], v[138:141], v[170:173], v[126:129]
	v_mfma_f32_16x16x32_bf16 v[122:125], v[142:145], v[166:169], v[122:125]
	v_mfma_f32_16x16x32_bf16 v[122:125], v[146:149], v[170:173], v[122:125]
	v_mfma_f32_16x16x32_bf16 v[110:113], v[134:137], v[174:177], v[110:113]
	v_mfma_f32_16x16x32_bf16 v[110:113], v[138:141], v[178:181], v[110:113]
	v_mfma_f32_16x16x32_bf16 v[106:109], v[142:145], v[174:177], v[106:109]
	v_mfma_f32_16x16x32_bf16 v[106:109], v[146:149], v[178:181], v[106:109]
	v_mfma_f32_16x16x32_bf16 v[94:97], v[134:137], v[182:185], v[94:97]
	v_mfma_f32_16x16x32_bf16 v[94:97], v[138:141], v[208:211], v[94:97]
	v_mfma_f32_16x16x32_bf16 v[90:93], v[142:145], v[182:185], v[90:93]
	v_mfma_f32_16x16x32_bf16 v[90:93], v[146:149], v[208:211], v[90:93]
	v_mfma_f32_16x16x32_bf16 v[78:81], v[134:137], v[214:217], v[78:81]
	v_mfma_f32_16x16x32_bf16 v[78:81], v[138:141], v[218:221], v[78:81]
	v_mfma_f32_16x16x32_bf16 v[74:77], v[142:145], v[214:217], v[74:77]
	v_mfma_f32_16x16x32_bf16 v[74:77], v[146:149], v[218:221], v[74:77]
	s_setprio 0
	s_setprio 1
	v_mfma_f32_16x16x32_bf16 v[118:121], v[150:153], v[166:169], v[118:121]
	v_mfma_f32_16x16x32_bf16 v[118:121], v[154:157], v[170:173], v[118:121]
	v_mfma_f32_16x16x32_bf16 v[114:117], v[158:161], v[166:169], v[114:117]
	v_mfma_f32_16x16x32_bf16 v[114:117], v[162:165], v[170:173], v[114:117]
	v_mfma_f32_16x16x32_bf16 v[102:105], v[150:153], v[174:177], v[102:105]
	v_mfma_f32_16x16x32_bf16 v[102:105], v[154:157], v[178:181], v[102:105]
	v_mfma_f32_16x16x32_bf16 v[98:101], v[158:161], v[174:177], v[98:101]
	v_mfma_f32_16x16x32_bf16 v[98:101], v[162:165], v[178:181], v[98:101]
	v_mfma_f32_16x16x32_bf16 v[86:89], v[150:153], v[182:185], v[86:89]
	v_mfma_f32_16x16x32_bf16 v[86:89], v[154:157], v[208:211], v[86:89]
	v_mfma_f32_16x16x32_bf16 v[82:85], v[158:161], v[182:185], v[82:85]
	v_mfma_f32_16x16x32_bf16 v[82:85], v[162:165], v[208:211], v[82:85]
	v_mfma_f32_16x16x32_bf16 v[70:73], v[150:153], v[214:217], v[70:73]
	v_mfma_f32_16x16x32_bf16 v[70:73], v[154:157], v[218:221], v[70:73]
	v_mfma_f32_16x16x32_bf16 v[66:69], v[158:161], v[214:217], v[66:69]
	v_mfma_f32_16x16x32_bf16 v[66:69], v[162:165], v[218:221], v[66:69]
	s_setprio 0
	s_barrier
	s_add_i32 s63, s52, s2
	v_lshl_add_u64 v[200:201], s[36:37], 0, v[188:189]
	s_mov_b32 m0, s63
	ds_read_b128 v[166:169], v206 offset:16384
	ds_read_b128 v[170:173], v206 offset:17408
	ds_read_b128 v[174:177], v206 offset:18432
	ds_read_b128 v[178:181], v206 offset:19456
	ds_read_b128 v[182:185], v206 offset:20480
	ds_read_b128 v[208:211], v206 offset:21504
	ds_read_b128 v[214:217], v206 offset:22528
	ds_read_b128 v[218:221], v206 offset:23552
	global_load_lds_dwordx4 v[200:201], off
	s_add_i32 m0, s63, 0x2000
	s_add_u32 s64, s36, 0x68000
	v_lshl_add_u64 v[222:223], s[36:37], 0, v[192:193]
	s_addc_u32 s65, s37, 0
	s_add_i32 s63, s53, s2
	global_load_lds_dwordx4 v[222:223], off
	v_lshl_add_u64 v[224:225], s[64:65], 0, v[188:189]
	s_mov_b32 m0, s63
	s_nop 0
	global_load_lds_dwordx4 v[224:225], off
	v_lshl_add_u64 v[224:225], s[64:65], 0, v[192:193]
	s_add_i32 m0, s63, 0x2000
	s_nop 0
	global_load_lds_dwordx4 v[224:225], off
	v_lshl_add_u64 v[224:225], s[38:39], 0, v[186:187]
	s_mov_b32 m0, s3
	s_nop 0
	global_load_lds_dwordx4 v[224:225], off
	v_lshl_add_u64 v[224:225], s[38:39], 0, v[190:191]
	s_mov_b32 m0, s33
	s_nop 0
	global_load_lds_dwordx4 v[224:225], off
	s_waitcnt vmcnt(8)
	s_waitcnt lgkmcnt(0)
	s_barrier
	s_setprio 1
	s_waitcnt lgkmcnt(0)
	v_mfma_f32_16x16x32_bf16 v[62:65], v[134:137], v[166:169], v[62:65]
	v_mfma_f32_16x16x32_bf16 v[62:65], v[138:141], v[170:173], v[62:65]
	v_mfma_f32_16x16x32_bf16 v[58:61], v[142:145], v[166:169], v[58:61]
	v_mfma_f32_16x16x32_bf16 v[58:61], v[146:149], v[170:173], v[58:61]
	v_mfma_f32_16x16x32_bf16 v[46:49], v[134:137], v[174:177], v[46:49]
	v_mfma_f32_16x16x32_bf16 v[46:49], v[138:141], v[178:181], v[46:49]
	v_mfma_f32_16x16x32_bf16 v[42:45], v[142:145], v[174:177], v[42:45]
	v_mfma_f32_16x16x32_bf16 v[42:45], v[146:149], v[178:181], v[42:45]
	v_mfma_f32_16x16x32_bf16 v[30:33], v[134:137], v[182:185], v[30:33]
	v_mfma_f32_16x16x32_bf16 v[30:33], v[138:141], v[208:211], v[30:33]
	v_mfma_f32_16x16x32_bf16 v[26:29], v[142:145], v[182:185], v[26:29]
	v_mfma_f32_16x16x32_bf16 v[26:29], v[146:149], v[208:211], v[26:29]
	v_mfma_f32_16x16x32_bf16 v[14:17], v[134:137], v[214:217], v[14:17]
	v_mfma_f32_16x16x32_bf16 v[14:17], v[138:141], v[218:221], v[14:17]
	v_mfma_f32_16x16x32_bf16 v[10:13], v[142:145], v[214:217], v[10:13]
	v_mfma_f32_16x16x32_bf16 v[10:13], v[146:149], v[218:221], v[10:13]
	s_setprio 0
	s_setprio 1
	v_mfma_f32_16x16x32_bf16 v[54:57], v[150:153], v[166:169], v[54:57]
	v_mfma_f32_16x16x32_bf16 v[54:57], v[154:157], v[170:173], v[54:57]
	v_mfma_f32_16x16x32_bf16 v[50:53], v[158:161], v[166:169], v[50:53]
	v_mfma_f32_16x16x32_bf16 v[50:53], v[162:165], v[170:173], v[50:53]
	v_mfma_f32_16x16x32_bf16 v[38:41], v[150:153], v[174:177], v[38:41]
	v_mfma_f32_16x16x32_bf16 v[38:41], v[154:157], v[178:181], v[38:41]
	v_mfma_f32_16x16x32_bf16 v[34:37], v[158:161], v[174:177], v[34:37]
	v_mfma_f32_16x16x32_bf16 v[34:37], v[162:165], v[178:181], v[34:37]
	v_mfma_f32_16x16x32_bf16 v[22:25], v[150:153], v[182:185], v[22:25]
	v_mfma_f32_16x16x32_bf16 v[22:25], v[154:157], v[208:211], v[22:25]
	v_mfma_f32_16x16x32_bf16 v[18:21], v[158:161], v[182:185], v[18:21]
	v_mfma_f32_16x16x32_bf16 v[18:21], v[162:165], v[208:211], v[18:21]
	v_mfma_f32_16x16x32_bf16 v[6:9], v[150:153], v[214:217], v[6:9]
	v_mfma_f32_16x16x32_bf16 v[6:9], v[154:157], v[218:221], v[6:9]
	v_mfma_f32_16x16x32_bf16 v[2:5], v[158:161], v[214:217], v[2:5]
	v_mfma_f32_16x16x32_bf16 v[2:5], v[162:165], v[218:221], v[2:5]
	s_setprio 0
	s_barrier
	s_add_i32 s63, 0, 0x18000
	s_add_i32 s64, 0, 0x1c000
	v_add_u32_e32 v146, s63, v202
	v_add_u32_e32 v162, s64, v202
	ds_read_b128 v[134:137], v146
	ds_read_b128 v[138:141], v146 offset:1024
	ds_read_b128 v[142:145], v146 offset:2048
	ds_read_b128 v[146:149], v146 offset:3072
	ds_read_b128 v[150:153], v162
	ds_read_b128 v[154:157], v162 offset:1024
	ds_read_b128 v[158:161], v162 offset:2048
	ds_read_b128 v[162:165], v162 offset:3072
	s_add_u32 s38, s38, 0x188000
	s_addc_u32 s39, s39, 0
	s_mov_b32 m0, s40
	v_lshl_add_u64 v[224:225], s[38:39], 0, v[186:187]
	ds_read_b128 v[166:169], v206 offset:32768
	ds_read_b128 v[170:173], v206 offset:33792
	ds_read_b128 v[174:177], v206 offset:34816
	ds_read_b128 v[178:181], v206 offset:35840
	ds_read_b128 v[182:185], v206 offset:36864
	ds_read_b128 v[208:211], v206 offset:37888
	ds_read_b128 v[214:217], v206 offset:38912
	ds_read_b128 v[218:221], v206 offset:39936
	global_load_lds_dwordx4 v[224:225], off
	v_lshl_add_u64 v[224:225], s[38:39], 0, v[190:191]
	s_mov_b32 m0, s41
	s_nop 0
	global_load_lds_dwordx4 v[224:225], off
	s_waitcnt vmcnt(8)
	s_waitcnt lgkmcnt(0)
	s_barrier
	s_setprio 1
	s_waitcnt lgkmcnt(0)
	v_mfma_f32_16x16x32_bf16 v[126:129], v[134:137], v[166:169], v[126:129]
	v_mfma_f32_16x16x32_bf16 v[126:129], v[138:141], v[170:173], v[126:129]
	v_mfma_f32_16x16x32_bf16 v[122:125], v[142:145], v[166:169], v[122:125]
	v_mfma_f32_16x16x32_bf16 v[122:125], v[146:149], v[170:173], v[122:125]
	v_mfma_f32_16x16x32_bf16 v[110:113], v[134:137], v[174:177], v[110:113]
	v_mfma_f32_16x16x32_bf16 v[110:113], v[138:141], v[178:181], v[110:113]
	v_mfma_f32_16x16x32_bf16 v[106:109], v[142:145], v[174:177], v[106:109]
	v_mfma_f32_16x16x32_bf16 v[106:109], v[146:149], v[178:181], v[106:109]
	v_mfma_f32_16x16x32_bf16 v[94:97], v[134:137], v[182:185], v[94:97]
	v_mfma_f32_16x16x32_bf16 v[94:97], v[138:141], v[208:211], v[94:97]
	v_mfma_f32_16x16x32_bf16 v[90:93], v[142:145], v[182:185], v[90:93]
	v_mfma_f32_16x16x32_bf16 v[90:93], v[146:149], v[208:211], v[90:93]
	v_mfma_f32_16x16x32_bf16 v[78:81], v[134:137], v[214:217], v[78:81]
	v_mfma_f32_16x16x32_bf16 v[78:81], v[138:141], v[218:221], v[78:81]
	v_mfma_f32_16x16x32_bf16 v[74:77], v[142:145], v[214:217], v[74:77]
	v_mfma_f32_16x16x32_bf16 v[74:77], v[146:149], v[218:221], v[74:77]
	s_setprio 0
	s_setprio 1
	v_mfma_f32_16x16x32_bf16 v[118:121], v[150:153], v[166:169], v[118:121]
	v_mfma_f32_16x16x32_bf16 v[118:121], v[154:157], v[170:173], v[118:121]
	v_mfma_f32_16x16x32_bf16 v[114:117], v[158:161], v[166:169], v[114:117]
	v_mfma_f32_16x16x32_bf16 v[114:117], v[162:165], v[170:173], v[114:117]
	v_mfma_f32_16x16x32_bf16 v[102:105], v[150:153], v[174:177], v[102:105]
	v_mfma_f32_16x16x32_bf16 v[102:105], v[154:157], v[178:181], v[102:105]
	v_mfma_f32_16x16x32_bf16 v[98:101], v[158:161], v[174:177], v[98:101]
	v_mfma_f32_16x16x32_bf16 v[98:101], v[162:165], v[178:181], v[98:101]
	v_mfma_f32_16x16x32_bf16 v[86:89], v[150:153], v[182:185], v[86:89]
	v_mfma_f32_16x16x32_bf16 v[86:89], v[154:157], v[208:211], v[86:89]
	v_mfma_f32_16x16x32_bf16 v[82:85], v[158:161], v[182:185], v[82:85]
	v_mfma_f32_16x16x32_bf16 v[82:85], v[162:165], v[208:211], v[82:85]
	v_mfma_f32_16x16x32_bf16 v[70:73], v[150:153], v[214:217], v[70:73]
	v_mfma_f32_16x16x32_bf16 v[70:73], v[154:157], v[218:221], v[70:73]
	v_mfma_f32_16x16x32_bf16 v[66:69], v[158:161], v[214:217], v[66:69]
	v_mfma_f32_16x16x32_bf16 v[66:69], v[162:165], v[218:221], v[66:69]
	s_setprio 0
	s_barrier
	s_add_i32 s38, s63, s2
	v_lshl_add_u64 v[200:201], v[200:201], 0, s[12:13]
	s_mov_b32 m0, s38
	ds_read_b128 v[166:169], v206 offset:49152
	ds_read_b128 v[170:173], v206 offset:50176
	ds_read_b128 v[174:177], v206 offset:51200
	ds_read_b128 v[178:181], v206 offset:52224
	ds_read_b128 v[182:185], v206 offset:53248
	ds_read_b128 v[208:211], v206 offset:54272
	ds_read_b128 v[214:217], v206 offset:55296
	ds_read_b128 v[218:221], v206 offset:56320
	global_load_lds_dwordx4 v[200:201], off
	s_add_i32 m0, s38, 0x2000
	s_add_u32 s36, s36, 0x68080
	v_lshl_add_u64 v[200:201], v[222:223], 0, s[12:13]
	s_addc_u32 s37, s37, 0
	s_add_i32 s38, s64, s2
	global_load_lds_dwordx4 v[200:201], off
	v_lshl_add_u64 v[200:201], s[36:37], 0, v[188:189]
	s_mov_b32 m0, s38
	s_nop 0
	global_load_lds_dwordx4 v[200:201], off
	v_lshl_add_u64 v[200:201], s[36:37], 0, v[192:193]
	s_add_i32 m0, s38, 0x2000
	s_nop 0
	global_load_lds_dwordx4 v[200:201], off
	v_lshl_add_u64 v[200:201], s[34:35], 0, v[186:187]
	s_mov_b32 m0, s50
	s_nop 0
	global_load_lds_dwordx4 v[200:201], off
	v_lshl_add_u64 v[200:201], s[34:35], 0, v[190:191]
	s_mov_b32 m0, s51
	s_nop 0
	global_load_lds_dwordx4 v[200:201], off
	s_waitcnt vmcnt(8)
	s_waitcnt lgkmcnt(0)
	s_barrier
	s_setprio 1
	s_waitcnt lgkmcnt(0)
	v_mfma_f32_16x16x32_bf16 v[62:65], v[134:137], v[166:169], v[62:65]
	v_mfma_f32_16x16x32_bf16 v[62:65], v[138:141], v[170:173], v[62:65]
	v_mfma_f32_16x16x32_bf16 v[58:61], v[142:145], v[166:169], v[58:61]
	v_mfma_f32_16x16x32_bf16 v[58:61], v[146:149], v[170:173], v[58:61]
	v_mfma_f32_16x16x32_bf16 v[46:49], v[134:137], v[174:177], v[46:49]
	v_mfma_f32_16x16x32_bf16 v[46:49], v[138:141], v[178:181], v[46:49]
	v_mfma_f32_16x16x32_bf16 v[42:45], v[142:145], v[174:177], v[42:45]
	v_mfma_f32_16x16x32_bf16 v[42:45], v[146:149], v[178:181], v[42:45]
	v_mfma_f32_16x16x32_bf16 v[30:33], v[134:137], v[182:185], v[30:33]
	v_mfma_f32_16x16x32_bf16 v[30:33], v[138:141], v[208:211], v[30:33]
	v_mfma_f32_16x16x32_bf16 v[26:29], v[142:145], v[182:185], v[26:29]
	v_mfma_f32_16x16x32_bf16 v[26:29], v[146:149], v[208:211], v[26:29]
	v_mfma_f32_16x16x32_bf16 v[14:17], v[134:137], v[214:217], v[14:17]
	v_mfma_f32_16x16x32_bf16 v[14:17], v[138:141], v[218:221], v[14:17]
	v_mfma_f32_16x16x32_bf16 v[10:13], v[142:145], v[214:217], v[10:13]
	v_mfma_f32_16x16x32_bf16 v[10:13], v[146:149], v[218:221], v[10:13]
	s_setprio 0
	s_setprio 1
	v_mfma_f32_16x16x32_bf16 v[54:57], v[150:153], v[166:169], v[54:57]
	v_mfma_f32_16x16x32_bf16 v[54:57], v[154:157], v[170:173], v[54:57]
	v_mfma_f32_16x16x32_bf16 v[50:53], v[158:161], v[166:169], v[50:53]
	v_mfma_f32_16x16x32_bf16 v[50:53], v[162:165], v[170:173], v[50:53]
	v_mfma_f32_16x16x32_bf16 v[38:41], v[150:153], v[174:177], v[38:41]
	v_mfma_f32_16x16x32_bf16 v[38:41], v[154:157], v[178:181], v[38:41]
	v_mfma_f32_16x16x32_bf16 v[34:37], v[158:161], v[174:177], v[34:37]
	v_mfma_f32_16x16x32_bf16 v[34:37], v[162:165], v[178:181], v[34:37]
	v_mfma_f32_16x16x32_bf16 v[22:25], v[150:153], v[182:185], v[22:25]
	v_mfma_f32_16x16x32_bf16 v[22:25], v[154:157], v[208:211], v[22:25]
	v_mfma_f32_16x16x32_bf16 v[18:21], v[158:161], v[182:185], v[18:21]
	v_mfma_f32_16x16x32_bf16 v[18:21], v[162:165], v[208:211], v[18:21]
	v_mfma_f32_16x16x32_bf16 v[6:9], v[150:153], v[214:217], v[6:9]
	v_mfma_f32_16x16x32_bf16 v[6:9], v[154:157], v[218:221], v[6:9]
	v_mfma_f32_16x16x32_bf16 v[2:5], v[158:161], v[214:217], v[2:5]
	v_mfma_f32_16x16x32_bf16 v[2:5], v[162:165], v[218:221], v[2:5]
	s_setprio 0
	s_barrier
	s_add_i32 s62, s62, 2
	s_add_u32 s30, s30, 0x100
	s_addc_u32 s31, s31, 0
	s_cmp_gt_u32 s62, 21
	s_cbranch_scc0 .LBB0_434
	s_and_b64 vcc, exec, s[14:15]
	s_cbranch_vccz .LBB0_437
	s_barrier

.LBB0_519:
	s_add_i32 s39, s56, 0xfffe8000
	s_and_b32 s38, s36, 0x100
	s_and_b32 s39, s39, 0x3e0000
	s_or_b32 s38, s38, s39
	s_add_u32 s57, s34, s38
	s_addc_u32 s59, s35, 0
	s_add_u32 s38, s36, 0x100
	s_addc_u32 s39, s37, 0
	s_add_i32 s41, s56, 0xffff8000
	s_and_b32 s40, s38, 0x100
	s_and_b32 s41, s41, 0x7e0000
	s_or_b32 s40, s41, s40
	s_add_u32 s40, s34, s40
	s_addc_u32 s41, s35, 0
	s_add_u32 s58, s53, s36
	s_addc_u32 s37, s54, s37
	s_add_i32 s42, s36, 0x180
	s_and_b32 s42, s42, 0x180
	s_and_b32 s43, s56, 0x7e0000
	s_or_b32 s42, s43, s42
	s_add_u32 s60, s34, s42
	s_addc_u32 s61, s35, 0
	s_cmpk_eq_i32 s36, 0x3f00
	s_cselect_b32 s43, s1, s41
	s_cselect_b32 s42, s21, s40
	s_cselect_b32 s41, s23, s37
	s_cselect_b32 s40, s22, s58
	s_cselect_b32 s37, s52, s61
	s_cselect_b32 s36, s31, s60
	s_add_i32 s60, 0, 0x10000
	v_add_u32_e32 v1, s60, v199
	ds_read_b128 v[130:133], v1
	ds_read_b128 v[134:137], v1 offset:1024
	ds_read_b128 v[138:141], v1 offset:2048
	ds_read_b128 v[142:145], v1 offset:3072
	ds_read_b128 v[146:149], v201
	ds_read_b128 v[150:153], v201 offset:1024
	ds_read_b128 v[154:157], v201 offset:2048
	ds_read_b128 v[158:161], v201 offset:3072
	s_add_u32 s58, s57, 0x10080
	s_addc_u32 s59, s59, 0
	v_lshl_add_u64 v[208:209], s[58:59], 0, v[178:179]
	s_add_i32 m0, s3, 0xc000
	ds_read_b128 v[162:165], v202
	ds_read_b128 v[166:169], v202 offset:1024
	ds_read_b128 v[170:173], v202 offset:2048
	ds_read_b128 v[174:177], v202 offset:3072
	ds_read_b128 v[186:189], v202 offset:4096
	ds_read_b128 v[190:193], v202 offset:5120
	ds_read_b128 v[194:197], v202 offset:6144
	ds_read_b128 v[204:207], v202 offset:7168
	global_load_lds_dwordx4 v[208:209], off
	v_lshl_add_u64 v[208:209], s[58:59], 0, v[182:183]
	s_add_i32 m0, s3, 0xe000
	s_nop 0
	global_load_lds_dwordx4 v[208:209], off
	s_waitcnt vmcnt(8)
	s_waitcnt lgkmcnt(0)
	s_barrier
	s_setprio 1
	s_waitcnt lgkmcnt(0)
	v_mfma_f32_16x16x32_bf16 v[126:129], v[130:133], v[162:165], v[126:129]
	v_mfma_f32_16x16x32_bf16 v[126:129], v[134:137], v[166:169], v[126:129]
	v_mfma_f32_16x16x32_bf16 v[122:125], v[138:141], v[162:165], v[122:125]
	v_mfma_f32_16x16x32_bf16 v[122:125], v[142:145], v[166:169], v[122:125]
	v_mfma_f32_16x16x32_bf16 v[110:113], v[130:133], v[170:173], v[110:113]
	v_mfma_f32_16x16x32_bf16 v[110:113], v[134:137], v[174:177], v[110:113]
	v_mfma_f32_16x16x32_bf16 v[106:109], v[138:141], v[170:173], v[106:109]
	v_mfma_f32_16x16x32_bf16 v[106:109], v[142:145], v[174:177], v[106:109]
	v_mfma_f32_16x16x32_bf16 v[94:97], v[130:133], v[186:189], v[94:97]
	v_mfma_f32_16x16x32_bf16 v[94:97], v[134:137], v[190:193], v[94:97]
	v_mfma_f32_16x16x32_bf16 v[90:93], v[138:141], v[186:189], v[90:93]
	v_mfma_f32_16x16x32_bf16 v[90:93], v[142:145], v[190:193], v[90:93]
	v_mfma_f32_16x16x32_bf16 v[78:81], v[130:133], v[194:197], v[78:81]
	v_mfma_f32_16x16x32_bf16 v[78:81], v[134:137], v[204:207], v[78:81]
	v_mfma_f32_16x16x32_bf16 v[74:77], v[138:141], v[194:197], v[74:77]
	v_mfma_f32_16x16x32_bf16 v[74:77], v[142:145], v[204:207], v[74:77]
	s_setprio 0
	s_setprio 1
	v_mfma_f32_16x16x32_bf16 v[118:121], v[146:149], v[162:165], v[118:121]
	v_mfma_f32_16x16x32_bf16 v[118:121], v[150:153], v[166:169], v[118:121]
	v_mfma_f32_16x16x32_bf16 v[114:117], v[154:157], v[162:165], v[114:117]
	v_mfma_f32_16x16x32_bf16 v[114:117], v[158:161], v[166:169], v[114:117]
	v_mfma_f32_16x16x32_bf16 v[102:105], v[146:149], v[170:173], v[102:105]
	v_mfma_f32_16x16x32_bf16 v[102:105], v[150:153], v[174:177], v[102:105]
	v_mfma_f32_16x16x32_bf16 v[98:101], v[154:157], v[170:173], v[98:101]
	v_mfma_f32_16x16x32_bf16 v[98:101], v[158:161], v[174:177], v[98:101]
	v_mfma_f32_16x16x32_bf16 v[86:89], v[146:149], v[186:189], v[86:89]
	v_mfma_f32_16x16x32_bf16 v[86:89], v[150:153], v[190:193], v[86:89]
	v_mfma_f32_16x16x32_bf16 v[82:85], v[154:157], v[186:189], v[82:85]
	v_mfma_f32_16x16x32_bf16 v[82:85], v[158:161], v[190:193], v[82:85]
	v_mfma_f32_16x16x32_bf16 v[70:73], v[146:149], v[194:197], v[70:73]
	v_mfma_f32_16x16x32_bf16 v[70:73], v[150:153], v[204:207], v[70:73]
	v_mfma_f32_16x16x32_bf16 v[66:69], v[154:157], v[194:197], v[66:69]
	v_mfma_f32_16x16x32_bf16 v[66:69], v[158:161], v[204:207], v[66:69]
	s_setprio 0
	s_barrier
	s_add_i32 s57, s60, s2
	v_lshl_add_u64 v[208:209], s[40:41], 0, v[180:181]
	s_mov_b32 m0, s57
	ds_read_b128 v[162:165], v202 offset:16384
	ds_read_b128 v[166:169], v202 offset:17408
	ds_read_b128 v[170:173], v202 offset:18432
	ds_read_b128 v[174:177], v202 offset:19456
	ds_read_b128 v[186:189], v202 offset:20480
	ds_read_b128 v[190:193], v202 offset:21504
	ds_read_b128 v[194:197], v202 offset:22528
	ds_read_b128 v[204:207], v202 offset:23552
	global_load_lds_dwordx4 v[208:209], off
	s_add_i32 m0, s57, 0x2000
	s_add_u32 s58, s40, 0x208000
	v_lshl_add_u64 v[210:211], s[40:41], 0, v[184:185]
	s_addc_u32 s59, s41, 0
	s_add_i32 s57, s49, s2
	global_load_lds_dwordx4 v[210:211], off
	v_lshl_add_u64 v[214:215], s[58:59], 0, v[180:181]
	s_mov_b32 m0, s57
	s_nop 0
	global_load_lds_dwordx4 v[214:215], off
	v_lshl_add_u64 v[214:215], s[58:59], 0, v[184:185]
	s_add_i32 m0, s57, 0x2000
	s_nop 0
	global_load_lds_dwordx4 v[214:215], off
	v_lshl_add_u64 v[214:215], s[42:43], 0, v[178:179]
	s_mov_b32 m0, s3
	s_nop 0
	global_load_lds_dwordx4 v[214:215], off
	v_lshl_add_u64 v[214:215], s[42:43], 0, v[182:183]
	s_mov_b32 m0, s33
	s_nop 0
	global_load_lds_dwordx4 v[214:215], off
	s_waitcnt vmcnt(8)
	s_waitcnt lgkmcnt(0)
	s_barrier
	s_setprio 1
	s_waitcnt lgkmcnt(0)
	v_mfma_f32_16x16x32_bf16 v[62:65], v[130:133], v[162:165], v[62:65]
	v_mfma_f32_16x16x32_bf16 v[62:65], v[134:137], v[166:169], v[62:65]
	v_mfma_f32_16x16x32_bf16 v[58:61], v[138:141], v[162:165], v[58:61]
	v_mfma_f32_16x16x32_bf16 v[58:61], v[142:145], v[166:169], v[58:61]
	v_mfma_f32_16x16x32_bf16 v[46:49], v[130:133], v[170:173], v[46:49]
	v_mfma_f32_16x16x32_bf16 v[46:49], v[134:137], v[174:177], v[46:49]
	v_mfma_f32_16x16x32_bf16 v[42:45], v[138:141], v[170:173], v[42:45]
	v_mfma_f32_16x16x32_bf16 v[42:45], v[142:145], v[174:177], v[42:45]
	v_mfma_f32_16x16x32_bf16 v[30:33], v[130:133], v[186:189], v[30:33]
	v_mfma_f32_16x16x32_bf16 v[30:33], v[134:137], v[190:193], v[30:33]
	v_mfma_f32_16x16x32_bf16 v[26:29], v[138:141], v[186:189], v[26:29]
	v_mfma_f32_16x16x32_bf16 v[26:29], v[142:145], v[190:193], v[26:29]
	v_mfma_f32_16x16x32_bf16 v[14:17], v[130:133], v[194:197], v[14:17]
	v_mfma_f32_16x16x32_bf16 v[14:17], v[134:137], v[204:207], v[14:17]
	v_mfma_f32_16x16x32_bf16 v[10:13], v[138:141], v[194:197], v[10:13]
	v_mfma_f32_16x16x32_bf16 v[10:13], v[142:145], v[204:207], v[10:13]
	s_setprio 0
	s_setprio 1
	v_mfma_f32_16x16x32_bf16 v[54:57], v[146:149], v[162:165], v[54:57]
	v_mfma_f32_16x16x32_bf16 v[54:57], v[150:153], v[166:169], v[54:57]
	v_mfma_f32_16x16x32_bf16 v[50:53], v[154:157], v[162:165], v[50:53]
	v_mfma_f32_16x16x32_bf16 v[50:53], v[158:161], v[166:169], v[50:53]
	v_mfma_f32_16x16x32_bf16 v[38:41], v[146:149], v[170:173], v[38:41]
	v_mfma_f32_16x16x32_bf16 v[38:41], v[150:153], v[174:177], v[38:41]
	v_mfma_f32_16x16x32_bf16 v[34:37], v[154:157], v[170:173], v[34:37]
	v_mfma_f32_16x16x32_bf16 v[34:37], v[158:161], v[174:177], v[34:37]
	v_mfma_f32_16x16x32_bf16 v[22:25], v[146:149], v[186:189], v[22:25]
	v_mfma_f32_16x16x32_bf16 v[22:25], v[150:153], v[190:193], v[22:25]
	v_mfma_f32_16x16x32_bf16 v[18:21], v[154:157], v[186:189], v[18:21]
	v_mfma_f32_16x16x32_bf16 v[18:21], v[158:161], v[190:193], v[18:21]
	v_mfma_f32_16x16x32_bf16 v[6:9], v[146:149], v[194:197], v[6:9]
	v_mfma_f32_16x16x32_bf16 v[6:9], v[150:153], v[204:207], v[6:9]
	v_mfma_f32_16x16x32_bf16 v[2:5], v[154:157], v[194:197], v[2:5]
	v_mfma_f32_16x16x32_bf16 v[2:5], v[158:161], v[204:207], v[2:5]
	s_setprio 0
	s_barrier
	s_add_i32 s57, 0, 0x18000
	v_add_u32_e32 v1, s57, v199
	s_add_i32 s58, 0, 0x1c000
	ds_read_b128 v[130:133], v1
	ds_read_b128 v[134:137], v1 offset:1024
	ds_read_b128 v[138:141], v1 offset:2048
	ds_read_b128 v[142:145], v1 offset:3072
	v_add_u32_e32 v1, s58, v199
	ds_read_b128 v[146:149], v1
	ds_read_b128 v[150:153], v1 offset:1024
	ds_read_b128 v[154:157], v1 offset:2048
	ds_read_b128 v[158:161], v1 offset:3072
	s_add_u32 s42, s42, 0x10000
	s_addc_u32 s43, s43, 0
	s_mov_b32 m0, s44
	v_lshl_add_u64 v[214:215], s[42:43], 0, v[178:179]
	ds_read_b128 v[162:165], v202 offset:32768
	ds_read_b128 v[166:169], v202 offset:33792
	ds_read_b128 v[170:173], v202 offset:34816
	ds_read_b128 v[174:177], v202 offset:35840
	ds_read_b128 v[186:189], v202 offset:36864
	ds_read_b128 v[190:193], v202 offset:37888
	ds_read_b128 v[194:197], v202 offset:38912
	ds_read_b128 v[204:207], v202 offset:39936
	global_load_lds_dwordx4 v[214:215], off
	v_lshl_add_u64 v[214:215], s[42:43], 0, v[182:183]
	s_mov_b32 m0, s45
	s_nop 0
	global_load_lds_dwordx4 v[214:215], off
	s_waitcnt vmcnt(8)
	s_waitcnt lgkmcnt(0)
	s_barrier
	s_setprio 1
	s_waitcnt lgkmcnt(0)
	v_mfma_f32_16x16x32_bf16 v[126:129], v[130:133], v[162:165], v[126:129]
	v_mfma_f32_16x16x32_bf16 v[126:129], v[134:137], v[166:169], v[126:129]
	v_mfma_f32_16x16x32_bf16 v[122:125], v[138:141], v[162:165], v[122:125]
	v_mfma_f32_16x16x32_bf16 v[122:125], v[142:145], v[166:169], v[122:125]
	v_mfma_f32_16x16x32_bf16 v[110:113], v[130:133], v[170:173], v[110:113]
	v_mfma_f32_16x16x32_bf16 v[110:113], v[134:137], v[174:177], v[110:113]
	v_mfma_f32_16x16x32_bf16 v[106:109], v[138:141], v[170:173], v[106:109]
	v_mfma_f32_16x16x32_bf16 v[106:109], v[142:145], v[174:177], v[106:109]
	v_mfma_f32_16x16x32_bf16 v[94:97], v[130:133], v[186:189], v[94:97]
	v_mfma_f32_16x16x32_bf16 v[94:97], v[134:137], v[190:193], v[94:97]
	v_mfma_f32_16x16x32_bf16 v[90:93], v[138:141], v[186:189], v[90:93]
	v_mfma_f32_16x16x32_bf16 v[90:93], v[142:145], v[190:193], v[90:93]
	v_mfma_f32_16x16x32_bf16 v[78:81], v[130:133], v[194:197], v[78:81]
	v_mfma_f32_16x16x32_bf16 v[78:81], v[134:137], v[204:207], v[78:81]
	v_mfma_f32_16x16x32_bf16 v[74:77], v[138:141], v[194:197], v[74:77]
	v_mfma_f32_16x16x32_bf16 v[74:77], v[142:145], v[204:207], v[74:77]
	s_setprio 0
	s_setprio 1
	v_mfma_f32_16x16x32_bf16 v[118:121], v[146:149], v[162:165], v[118:121]
	v_mfma_f32_16x16x32_bf16 v[118:121], v[150:153], v[166:169], v[118:121]
	v_mfma_f32_16x16x32_bf16 v[114:117], v[154:157], v[162:165], v[114:117]
	v_mfma_f32_16x16x32_bf16 v[114:117], v[158:161], v[166:169], v[114:117]
	v_mfma_f32_16x16x32_bf16 v[102:105], v[146:149], v[170:173], v[102:105]
	v_mfma_f32_16x16x32_bf16 v[102:105], v[150:153], v[174:177], v[102:105]
	v_mfma_f32_16x16x32_bf16 v[98:101], v[154:157], v[170:173], v[98:101]
	v_mfma_f32_16x16x32_bf16 v[98:101], v[158:161], v[174:177], v[98:101]
	v_mfma_f32_16x16x32_bf16 v[86:89], v[146:149], v[186:189], v[86:89]
	v_mfma_f32_16x16x32_bf16 v[86:89], v[150:153], v[190:193], v[86:89]
	v_mfma_f32_16x16x32_bf16 v[82:85], v[154:157], v[186:189], v[82:85]
	v_mfma_f32_16x16x32_bf16 v[82:85], v[158:161], v[190:193], v[82:85]
	v_mfma_f32_16x16x32_bf16 v[70:73], v[146:149], v[194:197], v[70:73]
	v_mfma_f32_16x16x32_bf16 v[70:73], v[150:153], v[204:207], v[70:73]
	v_mfma_f32_16x16x32_bf16 v[66:69], v[154:157], v[194:197], v[66:69]
	v_mfma_f32_16x16x32_bf16 v[66:69], v[158:161], v[204:207], v[66:69]
	s_setprio 0
	s_barrier
	s_add_i32 s42, s57, s2
	v_lshl_add_u64 v[208:209], v[208:209], 0, s[16:17]
	s_mov_b32 m0, s42
	ds_read_b128 v[162:165], v202 offset:49152
	ds_read_b128 v[166:169], v202 offset:50176
	ds_read_b128 v[170:173], v202 offset:51200
	ds_read_b128 v[174:177], v202 offset:52224
	ds_read_b128 v[186:189], v202 offset:53248
	ds_read_b128 v[190:193], v202 offset:54272
	ds_read_b128 v[194:197], v202 offset:55296
	ds_read_b128 v[204:207], v202 offset:56320
	global_load_lds_dwordx4 v[208:209], off
	s_add_i32 m0, s42, 0x2000
	s_add_u32 s40, s40, 0x208080
	v_lshl_add_u64 v[208:209], v[210:211], 0, s[16:17]
	s_addc_u32 s41, s41, 0
	s_add_i32 s42, s58, s2
	global_load_lds_dwordx4 v[208:209], off
	v_lshl_add_u64 v[208:209], s[40:41], 0, v[180:181]
	s_mov_b32 m0, s42
	s_nop 0
	global_load_lds_dwordx4 v[208:209], off
	v_lshl_add_u64 v[208:209], s[40:41], 0, v[184:185]
	s_add_i32 m0, s42, 0x2000
	s_nop 0
	global_load_lds_dwordx4 v[208:209], off
	v_lshl_add_u64 v[208:209], s[36:37], 0, v[178:179]
	s_mov_b32 m0, s47
	s_nop 0
	global_load_lds_dwordx4 v[208:209], off
	v_lshl_add_u64 v[208:209], s[36:37], 0, v[182:183]
	s_mov_b32 m0, s48
	s_nop 0
	global_load_lds_dwordx4 v[208:209], off
	s_waitcnt vmcnt(8)
	s_waitcnt lgkmcnt(0)
	s_barrier
	s_setprio 1
	s_waitcnt lgkmcnt(0)
	v_mfma_f32_16x16x32_bf16 v[62:65], v[130:133], v[162:165], v[62:65]
	v_mfma_f32_16x16x32_bf16 v[62:65], v[134:137], v[166:169], v[62:65]
	v_mfma_f32_16x16x32_bf16 v[58:61], v[138:141], v[162:165], v[58:61]
	v_mfma_f32_16x16x32_bf16 v[58:61], v[142:145], v[166:169], v[58:61]
	v_mfma_f32_16x16x32_bf16 v[46:49], v[130:133], v[170:173], v[46:49]
	v_mfma_f32_16x16x32_bf16 v[46:49], v[134:137], v[174:177], v[46:49]
	v_mfma_f32_16x16x32_bf16 v[42:45], v[138:141], v[170:173], v[42:45]
	v_mfma_f32_16x16x32_bf16 v[42:45], v[142:145], v[174:177], v[42:45]
	v_mfma_f32_16x16x32_bf16 v[30:33], v[130:133], v[186:189], v[30:33]
	v_mfma_f32_16x16x32_bf16 v[30:33], v[134:137], v[190:193], v[30:33]
	v_mfma_f32_16x16x32_bf16 v[26:29], v[138:141], v[186:189], v[26:29]
	v_mfma_f32_16x16x32_bf16 v[26:29], v[142:145], v[190:193], v[26:29]
	v_mfma_f32_16x16x32_bf16 v[14:17], v[130:133], v[194:197], v[14:17]
	v_mfma_f32_16x16x32_bf16 v[14:17], v[134:137], v[204:207], v[14:17]
	v_mfma_f32_16x16x32_bf16 v[10:13], v[138:141], v[194:197], v[10:13]
	v_mfma_f32_16x16x32_bf16 v[10:13], v[142:145], v[204:207], v[10:13]
	s_setprio 0
	s_setprio 1
	v_mfma_f32_16x16x32_bf16 v[54:57], v[146:149], v[162:165], v[54:57]
	v_mfma_f32_16x16x32_bf16 v[54:57], v[150:153], v[166:169], v[54:57]
	v_mfma_f32_16x16x32_bf16 v[50:53], v[154:157], v[162:165], v[50:53]
	v_mfma_f32_16x16x32_bf16 v[50:53], v[158:161], v[166:169], v[50:53]
	v_mfma_f32_16x16x32_bf16 v[38:41], v[146:149], v[170:173], v[38:41]
	v_mfma_f32_16x16x32_bf16 v[38:41], v[150:153], v[174:177], v[38:41]
	v_mfma_f32_16x16x32_bf16 v[34:37], v[154:157], v[170:173], v[34:37]
	v_mfma_f32_16x16x32_bf16 v[34:37], v[158:161], v[174:177], v[34:37]
	v_mfma_f32_16x16x32_bf16 v[22:25], v[146:149], v[186:189], v[22:25]
	v_mfma_f32_16x16x32_bf16 v[22:25], v[150:153], v[190:193], v[22:25]
	v_mfma_f32_16x16x32_bf16 v[18:21], v[154:157], v[186:189], v[18:21]
	v_mfma_f32_16x16x32_bf16 v[18:21], v[158:161], v[190:193], v[18:21]
	v_mfma_f32_16x16x32_bf16 v[6:9], v[146:149], v[194:197], v[6:9]
	v_mfma_f32_16x16x32_bf16 v[6:9], v[150:153], v[204:207], v[6:9]
	v_mfma_f32_16x16x32_bf16 v[2:5], v[154:157], v[194:197], v[2:5]
	v_mfma_f32_16x16x32_bf16 v[2:5], v[158:161], v[204:207], v[2:5]
	s_setprio 0
	s_barrier
	s_add_i32 s55, s55, 2
	s_add_i32 s56, s56, 0x10000
	s_cmpk_gt_u32 s55, 0x7d
	s_mov_b64 s[36:37], s[38:39]
	s_cbranch_scc0 .LBB0_519
	s_and_b64 vcc, exec, s[18:19]
	s_cbranch_vccz .LBB0_522
	s_barrier

.LBB0_612:
	ds_read_b128 v[166:169], v152
	ds_read_b128 v[170:173], v152 offset:1024
	ds_read_b128 v[174:177], v152 offset:2048
	ds_read_b128 v[178:181], v152 offset:3072
	ds_read_b128 v[182:185], v153
	ds_read_b128 v[186:189], v153 offset:1024
	ds_read_b128 v[190:193], v153 offset:2048
	ds_read_b128 v[194:197], v153 offset:3072
	s_add_u32 s26, s4, s22
	s_addc_u32 s27, s5, s23
	s_add_u32 s30, s26, 0x100
	s_addc_u32 s31, s27, 0
	s_add_u32 s28, s52, s22
	s_addc_u32 s29, s53, s23
	s_add_u32 s26, s26, 0x180
	s_addc_u32 s27, s27, 0
	s_cmpk_eq_i32 s22, 0x1f00
	s_cselect_b32 s27, s51, s27
	s_cselect_b32 s26, s50, s26
	s_cselect_b32 s29, s21, s29
	s_cselect_b32 s28, s20, s28
	s_cselect_b32 s31, s19, s31
	s_cselect_b32 s30, s18, s30
	s_mov_b32 m0, s37
	v_lshl_add_u64 v[210:211], v[148:149], 0, s[22:23]
	ds_read_b128 v[198:201], v154
	ds_read_b128 v[202:205], v154 offset:1024
	ds_read_b128 v[206:209], v154 offset:2048
	ds_read_b128 v[214:217], v154 offset:3072
	ds_read_b128 v[218:221], v154 offset:4096
	ds_read_b128 v[222:225], v154 offset:5120
	ds_read_b128 v[226:229], v154 offset:6144
	ds_read_b128 v[230:233], v154 offset:7168
	global_load_lds_dwordx4 v[210:211], off
	v_lshl_add_u64 v[210:211], v[150:151], 0, s[22:23]
	s_mov_b32 m0, s38
	s_nop 0
	global_load_lds_dwordx4 v[210:211], off
	s_waitcnt vmcnt(8)
	s_waitcnt lgkmcnt(0)
	s_barrier
	s_setprio 1
	s_waitcnt lgkmcnt(0)
	v_mfma_f32_16x16x32_bf16 v[126:129], v[166:169], v[198:201], v[126:129]
	v_mfma_f32_16x16x32_bf16 v[126:129], v[170:173], v[202:205], v[126:129]
	v_mfma_f32_16x16x32_bf16 v[122:125], v[174:177], v[198:201], v[122:125]
	v_mfma_f32_16x16x32_bf16 v[122:125], v[178:181], v[202:205], v[122:125]
	v_mfma_f32_16x16x32_bf16 v[110:113], v[166:169], v[206:209], v[110:113]
	v_mfma_f32_16x16x32_bf16 v[110:113], v[170:173], v[214:217], v[110:113]
	v_mfma_f32_16x16x32_bf16 v[106:109], v[174:177], v[206:209], v[106:109]
	v_mfma_f32_16x16x32_bf16 v[106:109], v[178:181], v[214:217], v[106:109]
	v_mfma_f32_16x16x32_bf16 v[94:97], v[166:169], v[218:221], v[94:97]
	v_mfma_f32_16x16x32_bf16 v[94:97], v[170:173], v[222:225], v[94:97]
	v_mfma_f32_16x16x32_bf16 v[90:93], v[174:177], v[218:221], v[90:93]
	v_mfma_f32_16x16x32_bf16 v[90:93], v[178:181], v[222:225], v[90:93]
	v_mfma_f32_16x16x32_bf16 v[78:81], v[166:169], v[226:229], v[78:81]
	v_mfma_f32_16x16x32_bf16 v[78:81], v[170:173], v[230:233], v[78:81]
	v_mfma_f32_16x16x32_bf16 v[74:77], v[174:177], v[226:229], v[74:77]
	v_mfma_f32_16x16x32_bf16 v[74:77], v[178:181], v[230:233], v[74:77]
	s_setprio 0
	s_setprio 1
	v_mfma_f32_16x16x32_bf16 v[118:121], v[182:185], v[198:201], v[118:121]
	v_mfma_f32_16x16x32_bf16 v[118:121], v[186:189], v[202:205], v[118:121]
	v_mfma_f32_16x16x32_bf16 v[114:117], v[190:193], v[198:201], v[114:117]
	v_mfma_f32_16x16x32_bf16 v[114:117], v[194:197], v[202:205], v[114:117]
	v_mfma_f32_16x16x32_bf16 v[102:105], v[182:185], v[206:209], v[102:105]
	v_mfma_f32_16x16x32_bf16 v[102:105], v[186:189], v[214:217], v[102:105]
	v_mfma_f32_16x16x32_bf16 v[98:101], v[190:193], v[206:209], v[98:101]
	v_mfma_f32_16x16x32_bf16 v[98:101], v[194:197], v[214:217], v[98:101]
	v_mfma_f32_16x16x32_bf16 v[86:89], v[182:185], v[218:221], v[86:89]
	v_mfma_f32_16x16x32_bf16 v[86:89], v[186:189], v[222:225], v[86:89]
	v_mfma_f32_16x16x32_bf16 v[82:85], v[190:193], v[218:221], v[82:85]
	v_mfma_f32_16x16x32_bf16 v[82:85], v[194:197], v[222:225], v[82:85]
	v_mfma_f32_16x16x32_bf16 v[70:73], v[182:185], v[226:229], v[70:73]
	v_mfma_f32_16x16x32_bf16 v[70:73], v[186:189], v[230:233], v[70:73]
	v_mfma_f32_16x16x32_bf16 v[66:69], v[190:193], v[226:229], v[66:69]
	v_mfma_f32_16x16x32_bf16 v[66:69], v[194:197], v[230:233], v[66:69]
	s_setprio 0
	s_barrier
	s_mov_b32 m0, s39
	v_lshl_add_u64 v[210:211], s[28:29], 0, v[132:133]
	s_add_u32 s56, s28, 0x108000
	ds_read_b128 v[198:201], v154 offset:16384
	ds_read_b128 v[202:205], v154 offset:17408
	ds_read_b128 v[206:209], v154 offset:18432
	ds_read_b128 v[214:217], v154 offset:19456
	ds_read_b128 v[218:221], v154 offset:20480
	ds_read_b128 v[222:225], v154 offset:21504
	ds_read_b128 v[226:229], v154 offset:22528
	ds_read_b128 v[230:233], v154 offset:23552
	global_load_lds_dwordx4 v[210:211], off
	v_lshl_add_u64 v[234:235], s[28:29], 0, v[136:137]
	s_mov_b32 m0, s40
	s_addc_u32 s57, s29, 0
	global_load_lds_dwordx4 v[234:235], off
	v_lshl_add_u64 v[236:237], s[56:57], 0, v[132:133]
	s_mov_b32 m0, s41
	s_nop 0
	global_load_lds_dwordx4 v[236:237], off
	v_lshl_add_u64 v[236:237], s[56:57], 0, v[136:137]
	s_mov_b32 m0, s42
	s_nop 0
	global_load_lds_dwordx4 v[236:237], off
	v_lshl_add_u64 v[236:237], s[30:31], 0, v[130:131]
	s_mov_b32 m0, s2
	s_nop 0
	global_load_lds_dwordx4 v[236:237], off
	v_lshl_add_u64 v[236:237], s[30:31], 0, v[134:135]
	s_mov_b32 m0, s3
	s_nop 0
	global_load_lds_dwordx4 v[236:237], off
	s_waitcnt vmcnt(8)
	s_waitcnt lgkmcnt(0)
	s_barrier
	s_setprio 1
	s_waitcnt lgkmcnt(0)
	v_mfma_f32_16x16x32_bf16 v[62:65], v[166:169], v[198:201], v[62:65]
	v_mfma_f32_16x16x32_bf16 v[62:65], v[170:173], v[202:205], v[62:65]
	v_mfma_f32_16x16x32_bf16 v[58:61], v[174:177], v[198:201], v[58:61]
	v_mfma_f32_16x16x32_bf16 v[58:61], v[178:181], v[202:205], v[58:61]
	v_mfma_f32_16x16x32_bf16 v[46:49], v[166:169], v[206:209], v[46:49]
	v_mfma_f32_16x16x32_bf16 v[46:49], v[170:173], v[214:217], v[46:49]
	v_mfma_f32_16x16x32_bf16 v[42:45], v[174:177], v[206:209], v[42:45]
	v_mfma_f32_16x16x32_bf16 v[42:45], v[178:181], v[214:217], v[42:45]
	v_mfma_f32_16x16x32_bf16 v[30:33], v[166:169], v[218:221], v[30:33]
	v_mfma_f32_16x16x32_bf16 v[30:33], v[170:173], v[222:225], v[30:33]
	v_mfma_f32_16x16x32_bf16 v[26:29], v[174:177], v[218:221], v[26:29]
	v_mfma_f32_16x16x32_bf16 v[26:29], v[178:181], v[222:225], v[26:29]
	v_mfma_f32_16x16x32_bf16 v[14:17], v[166:169], v[226:229], v[14:17]
	v_mfma_f32_16x16x32_bf16 v[14:17], v[170:173], v[230:233], v[14:17]
	v_mfma_f32_16x16x32_bf16 v[10:13], v[174:177], v[226:229], v[10:13]
	v_mfma_f32_16x16x32_bf16 v[10:13], v[178:181], v[230:233], v[10:13]
	s_setprio 0
	s_setprio 1
	v_mfma_f32_16x16x32_bf16 v[54:57], v[182:185], v[198:201], v[54:57]
	v_mfma_f32_16x16x32_bf16 v[54:57], v[186:189], v[202:205], v[54:57]
	v_mfma_f32_16x16x32_bf16 v[50:53], v[190:193], v[198:201], v[50:53]
	v_mfma_f32_16x16x32_bf16 v[50:53], v[194:197], v[202:205], v[50:53]
	v_mfma_f32_16x16x32_bf16 v[38:41], v[182:185], v[206:209], v[38:41]
	v_mfma_f32_16x16x32_bf16 v[38:41], v[186:189], v[214:217], v[38:41]
	v_mfma_f32_16x16x32_bf16 v[34:37], v[190:193], v[206:209], v[34:37]
	v_mfma_f32_16x16x32_bf16 v[34:37], v[194:197], v[214:217], v[34:37]
	v_mfma_f32_16x16x32_bf16 v[22:25], v[182:185], v[218:221], v[22:25]
	v_mfma_f32_16x16x32_bf16 v[22:25], v[186:189], v[222:225], v[22:25]
	v_mfma_f32_16x16x32_bf16 v[18:21], v[190:193], v[218:221], v[18:21]
	v_mfma_f32_16x16x32_bf16 v[18:21], v[194:197], v[222:225], v[18:21]
	v_mfma_f32_16x16x32_bf16 v[6:9], v[182:185], v[226:229], v[6:9]
	v_mfma_f32_16x16x32_bf16 v[6:9], v[186:189], v[230:233], v[6:9]
	v_mfma_f32_16x16x32_bf16 v[2:5], v[190:193], v[226:229], v[2:5]
	v_mfma_f32_16x16x32_bf16 v[2:5], v[194:197], v[230:233], v[2:5]
	s_setprio 0
	s_barrier
	ds_read_b128 v[166:169], v156
	ds_read_b128 v[170:173], v156 offset:1024
	ds_read_b128 v[174:177], v156 offset:2048
	ds_read_b128 v[178:181], v156 offset:3072
	ds_read_b128 v[182:185], v157
	ds_read_b128 v[186:189], v157 offset:1024
	ds_read_b128 v[190:193], v157 offset:2048
	ds_read_b128 v[194:197], v157 offset:3072
	s_add_u32 s30, s30, 0x108000
	s_addc_u32 s31, s31, 0
	s_mov_b32 m0, s33
	v_lshl_add_u64 v[236:237], s[30:31], 0, v[130:131]
	ds_read_b128 v[198:201], v154 offset:32768
	ds_read_b128 v[202:205], v154 offset:33792
	ds_read_b128 v[206:209], v154 offset:34816
	ds_read_b128 v[214:217], v154 offset:35840
	ds_read_b128 v[218:221], v154 offset:36864
	ds_read_b128 v[222:225], v154 offset:37888
	ds_read_b128 v[226:229], v154 offset:38912
	ds_read_b128 v[230:233], v154 offset:39936
	global_load_lds_dwordx4 v[236:237], off
	v_lshl_add_u64 v[236:237], s[30:31], 0, v[134:135]
	s_mov_b32 m0, s34
	s_nop 0
	global_load_lds_dwordx4 v[236:237], off
	s_waitcnt vmcnt(8)
	s_waitcnt lgkmcnt(0)
	s_barrier
	s_setprio 1
	s_waitcnt lgkmcnt(0)
	v_mfma_f32_16x16x32_bf16 v[126:129], v[166:169], v[198:201], v[126:129]
	v_mfma_f32_16x16x32_bf16 v[126:129], v[170:173], v[202:205], v[126:129]
	v_mfma_f32_16x16x32_bf16 v[122:125], v[174:177], v[198:201], v[122:125]
	v_mfma_f32_16x16x32_bf16 v[122:125], v[178:181], v[202:205], v[122:125]
	v_mfma_f32_16x16x32_bf16 v[110:113], v[166:169], v[206:209], v[110:113]
	v_mfma_f32_16x16x32_bf16 v[110:113], v[170:173], v[214:217], v[110:113]
	v_mfma_f32_16x16x32_bf16 v[106:109], v[174:177], v[206:209], v[106:109]
	v_mfma_f32_16x16x32_bf16 v[106:109], v[178:181], v[214:217], v[106:109]
	v_mfma_f32_16x16x32_bf16 v[94:97], v[166:169], v[218:221], v[94:97]
	v_mfma_f32_16x16x32_bf16 v[94:97], v[170:173], v[222:225], v[94:97]
	v_mfma_f32_16x16x32_bf16 v[90:93], v[174:177], v[218:221], v[90:93]
	v_mfma_f32_16x16x32_bf16 v[90:93], v[178:181], v[222:225], v[90:93]
	v_mfma_f32_16x16x32_bf16 v[78:81], v[166:169], v[226:229], v[78:81]
	v_mfma_f32_16x16x32_bf16 v[78:81], v[170:173], v[230:233], v[78:81]
	v_mfma_f32_16x16x32_bf16 v[74:77], v[174:177], v[226:229], v[74:77]
	v_mfma_f32_16x16x32_bf16 v[74:77], v[178:181], v[230:233], v[74:77]
	s_setprio 0
	s_setprio 1
	v_mfma_f32_16x16x32_bf16 v[118:121], v[182:185], v[198:201], v[118:121]
	v_mfma_f32_16x16x32_bf16 v[118:121], v[186:189], v[202:205], v[118:121]
	v_mfma_f32_16x16x32_bf16 v[114:117], v[190:193], v[198:201], v[114:117]
	v_mfma_f32_16x16x32_bf16 v[114:117], v[194:197], v[202:205], v[114:117]
	v_mfma_f32_16x16x32_bf16 v[102:105], v[182:185], v[206:209], v[102:105]
	v_mfma_f32_16x16x32_bf16 v[102:105], v[186:189], v[214:217], v[102:105]
	v_mfma_f32_16x16x32_bf16 v[98:101], v[190:193], v[206:209], v[98:101]
	v_mfma_f32_16x16x32_bf16 v[98:101], v[194:197], v[214:217], v[98:101]
	v_mfma_f32_16x16x32_bf16 v[86:89], v[182:185], v[218:221], v[86:89]
	v_mfma_f32_16x16x32_bf16 v[86:89], v[186:189], v[222:225], v[86:89]
	v_mfma_f32_16x16x32_bf16 v[82:85], v[190:193], v[218:221], v[82:85]
	v_mfma_f32_16x16x32_bf16 v[82:85], v[194:197], v[222:225], v[82:85]
	v_mfma_f32_16x16x32_bf16 v[70:73], v[182:185], v[226:229], v[70:73]
	v_mfma_f32_16x16x32_bf16 v[70:73], v[186:189], v[230:233], v[70:73]
	v_mfma_f32_16x16x32_bf16 v[66:69], v[190:193], v[226:229], v[66:69]
	v_mfma_f32_16x16x32_bf16 v[66:69], v[194:197], v[230:233], v[66:69]
	s_setprio 0
	s_barrier
	s_mov_b32 m0, s43
	v_lshl_add_u64 v[210:211], v[210:211], 0, s[14:15]
	s_add_u32 s28, s28, 0x108080
	ds_read_b128 v[198:201], v154 offset:49152
	ds_read_b128 v[202:205], v154 offset:50176
	ds_read_b128 v[206:209], v154 offset:51200
	ds_read_b128 v[214:217], v154 offset:52224
	ds_read_b128 v[218:221], v154 offset:53248
	ds_read_b128 v[222:225], v154 offset:54272
	ds_read_b128 v[226:229], v154 offset:55296
	ds_read_b128 v[230:233], v154 offset:56320
	global_load_lds_dwordx4 v[210:211], off
	v_lshl_add_u64 v[210:211], v[234:235], 0, s[14:15]
	s_mov_b32 m0, s44
	s_addc_u32 s29, s29, 0
	global_load_lds_dwordx4 v[210:211], off
	v_lshl_add_u64 v[210:211], s[28:29], 0, v[132:133]
	s_mov_b32 m0, s45
	s_nop 0
	global_load_lds_dwordx4 v[210:211], off
	v_lshl_add_u64 v[210:211], s[28:29], 0, v[136:137]
	s_mov_b32 m0, s46
	s_nop 0
	global_load_lds_dwordx4 v[210:211], off
	v_lshl_add_u64 v[210:211], s[26:27], 0, v[130:131]
	s_mov_b32 m0, s35
	s_nop 0
	global_load_lds_dwordx4 v[210:211], off
	v_lshl_add_u64 v[210:211], s[26:27], 0, v[134:135]
	s_mov_b32 m0, s36
	s_nop 0
	global_load_lds_dwordx4 v[210:211], off
	s_waitcnt vmcnt(8)
	s_waitcnt lgkmcnt(0)
	s_barrier
	s_setprio 1
	s_waitcnt lgkmcnt(0)
	v_mfma_f32_16x16x32_bf16 v[62:65], v[166:169], v[198:201], v[62:65]
	v_mfma_f32_16x16x32_bf16 v[62:65], v[170:173], v[202:205], v[62:65]
	v_mfma_f32_16x16x32_bf16 v[58:61], v[174:177], v[198:201], v[58:61]
	v_mfma_f32_16x16x32_bf16 v[58:61], v[178:181], v[202:205], v[58:61]
	v_mfma_f32_16x16x32_bf16 v[46:49], v[166:169], v[206:209], v[46:49]
	v_mfma_f32_16x16x32_bf16 v[46:49], v[170:173], v[214:217], v[46:49]
	v_mfma_f32_16x16x32_bf16 v[42:45], v[174:177], v[206:209], v[42:45]
	v_mfma_f32_16x16x32_bf16 v[42:45], v[178:181], v[214:217], v[42:45]
	v_mfma_f32_16x16x32_bf16 v[30:33], v[166:169], v[218:221], v[30:33]
	v_mfma_f32_16x16x32_bf16 v[30:33], v[170:173], v[222:225], v[30:33]
	v_mfma_f32_16x16x32_bf16 v[26:29], v[174:177], v[218:221], v[26:29]
	v_mfma_f32_16x16x32_bf16 v[26:29], v[178:181], v[222:225], v[26:29]
	v_mfma_f32_16x16x32_bf16 v[14:17], v[166:169], v[226:229], v[14:17]
	v_mfma_f32_16x16x32_bf16 v[14:17], v[170:173], v[230:233], v[14:17]
	v_mfma_f32_16x16x32_bf16 v[10:13], v[174:177], v[226:229], v[10:13]
	v_mfma_f32_16x16x32_bf16 v[10:13], v[178:181], v[230:233], v[10:13]
	s_setprio 0
	s_setprio 1
	v_mfma_f32_16x16x32_bf16 v[54:57], v[182:185], v[198:201], v[54:57]
	v_mfma_f32_16x16x32_bf16 v[54:57], v[186:189], v[202:205], v[54:57]
	v_mfma_f32_16x16x32_bf16 v[50:53], v[190:193], v[198:201], v[50:53]
	v_mfma_f32_16x16x32_bf16 v[50:53], v[194:197], v[202:205], v[50:53]
	v_mfma_f32_16x16x32_bf16 v[38:41], v[182:185], v[206:209], v[38:41]
	v_mfma_f32_16x16x32_bf16 v[38:41], v[186:189], v[214:217], v[38:41]
	v_mfma_f32_16x16x32_bf16 v[34:37], v[190:193], v[206:209], v[34:37]
	v_mfma_f32_16x16x32_bf16 v[34:37], v[194:197], v[214:217], v[34:37]
	v_mfma_f32_16x16x32_bf16 v[22:25], v[182:185], v[218:221], v[22:25]
	v_mfma_f32_16x16x32_bf16 v[22:25], v[186:189], v[222:225], v[22:25]
	v_mfma_f32_16x16x32_bf16 v[18:21], v[190:193], v[218:221], v[18:21]
	v_mfma_f32_16x16x32_bf16 v[18:21], v[194:197], v[222:225], v[18:21]
	v_mfma_f32_16x16x32_bf16 v[6:9], v[182:185], v[226:229], v[6:9]
	v_mfma_f32_16x16x32_bf16 v[6:9], v[186:189], v[230:233], v[6:9]
	v_mfma_f32_16x16x32_bf16 v[2:5], v[190:193], v[226:229], v[2:5]
	v_mfma_f32_16x16x32_bf16 v[2:5], v[194:197], v[230:233], v[2:5]
	s_setprio 0
	s_barrier
	s_add_i32 s54, s54, 2
	s_add_u32 s22, s22, 0x100
	s_addc_u32 s23, s23, 0
	s_cmp_gt_u32 s54, 61
	s_cbranch_scc0 .LBB0_612
	s_and_b64 vcc, exec, s[16:17]
	s_cbranch_vccz .LBB0_615
	s_barrier

.LBB0_844:
	s_add_i32 s35, s52, 0xfffe8000
	s_and_b32 s34, s30, 0x100
	s_and_b32 s35, s35, 0x3e0000
	s_or_b32 s34, s34, s35
	s_add_u32 s53, s28, s34
	s_addc_u32 s55, s29, 0
	s_add_u32 s34, s30, 0x100
	s_addc_u32 s35, s31, 0
	s_add_i32 s37, s52, 0xffff8000
	s_and_b32 s36, s34, 0x100
	s_and_b32 s37, s37, 0x7e0000
	s_or_b32 s36, s37, s36
	s_add_u32 s36, s28, s36
	s_addc_u32 s37, s29, 0
	s_add_u32 s54, s49, s30
	s_addc_u32 s31, s50, s31
	s_add_i32 s38, s30, 0x180
	s_and_b32 s38, s38, 0x180
	s_and_b32 s39, s52, 0x7e0000
	s_or_b32 s38, s39, s38
	s_add_u32 s56, s28, s38
	s_addc_u32 s57, s29, 0
	s_cmpk_eq_i32 s30, 0x3f00
	s_cselect_b32 s39, s1, s37
	s_cselect_b32 s38, s21, s36
	s_cselect_b32 s37, s23, s31
	s_cselect_b32 s36, s22, s54
	s_cselect_b32 s31, s48, s57
	s_cselect_b32 s30, s27, s56
	s_add_i32 s56, 0, 0x10000
	v_add_u32_e32 v124, s56, v211
	ds_read_b128 v[104:107], v124
	ds_read_b128 v[108:111], v124 offset:1024
	ds_read_b128 v[120:123], v124 offset:2048
	ds_read_b128 v[124:127], v124 offset:3072
	ds_read_b128 v[144:147], v214
	ds_read_b128 v[148:151], v214 offset:1024
	ds_read_b128 v[152:155], v214 offset:2048
	ds_read_b128 v[156:159], v214 offset:3072
	s_add_u32 s54, s53, 0x10080
	s_addc_u32 s55, s55, 0
	v_lshl_add_u64 v[200:201], s[54:55], 0, v[184:185]
	s_add_i32 m0, s3, 0xc000
	ds_read_b128 v[160:163], v215
	ds_read_b128 v[164:167], v215 offset:1024
	ds_read_b128 v[168:171], v215 offset:2048
	ds_read_b128 v[172:175], v215 offset:3072
	ds_read_b128 v[176:179], v215 offset:4096
	ds_read_b128 v[180:183], v215 offset:5120
	ds_read_b128 v[192:195], v215 offset:6144
	ds_read_b128 v[196:199], v215 offset:7168
	global_load_lds_dwordx4 v[200:201], off
	v_lshl_add_u64 v[200:201], s[54:55], 0, v[188:189]
	s_add_i32 m0, s3, 0xe000
	s_nop 0
	global_load_lds_dwordx4 v[200:201], off
	s_waitcnt vmcnt(8)
	s_waitcnt lgkmcnt(0)
	s_barrier
	s_setprio 1
	s_waitcnt lgkmcnt(0)
	v_mfma_f32_16x16x32_bf16 v[140:143], v[104:107], v[160:163], v[140:143]
	v_mfma_f32_16x16x32_bf16 v[140:143], v[108:111], v[164:167], v[140:143]
	v_mfma_f32_16x16x32_bf16 v[136:139], v[120:123], v[160:163], v[136:139]
	v_mfma_f32_16x16x32_bf16 v[136:139], v[124:127], v[164:167], v[136:139]
	v_mfma_f32_16x16x32_bf16 v[116:119], v[104:107], v[168:171], v[116:119]
	v_mfma_f32_16x16x32_bf16 v[116:119], v[108:111], v[172:175], v[116:119]
	v_mfma_f32_16x16x32_bf16 v[112:115], v[120:123], v[168:171], v[112:115]
	v_mfma_f32_16x16x32_bf16 v[112:115], v[124:127], v[172:175], v[112:115]
	v_mfma_f32_16x16x32_bf16 v[92:95], v[104:107], v[176:179], v[92:95]
	v_mfma_f32_16x16x32_bf16 v[92:95], v[108:111], v[180:183], v[92:95]
	v_mfma_f32_16x16x32_bf16 v[88:91], v[120:123], v[176:179], v[88:91]
	v_mfma_f32_16x16x32_bf16 v[88:91], v[124:127], v[180:183], v[88:91]
	v_mfma_f32_16x16x32_bf16 v[76:79], v[104:107], v[192:195], v[76:79]
	v_mfma_f32_16x16x32_bf16 v[76:79], v[108:111], v[196:199], v[76:79]
	v_mfma_f32_16x16x32_bf16 v[72:75], v[120:123], v[192:195], v[72:75]
	v_mfma_f32_16x16x32_bf16 v[72:75], v[124:127], v[196:199], v[72:75]
	s_setprio 0
	s_setprio 1
	v_mfma_f32_16x16x32_bf16 v[132:135], v[144:147], v[160:163], v[132:135]
	v_mfma_f32_16x16x32_bf16 v[132:135], v[148:151], v[164:167], v[132:135]
	v_mfma_f32_16x16x32_bf16 v[128:131], v[152:155], v[160:163], v[128:131]
	v_mfma_f32_16x16x32_bf16 v[128:131], v[156:159], v[164:167], v[128:131]
	v_mfma_f32_16x16x32_bf16 v[100:103], v[144:147], v[168:171], v[100:103]
	v_mfma_f32_16x16x32_bf16 v[100:103], v[148:151], v[172:175], v[100:103]
	v_mfma_f32_16x16x32_bf16 v[96:99], v[152:155], v[168:171], v[96:99]
	v_mfma_f32_16x16x32_bf16 v[96:99], v[156:159], v[172:175], v[96:99]
	v_mfma_f32_16x16x32_bf16 v[84:87], v[144:147], v[176:179], v[84:87]
	v_mfma_f32_16x16x32_bf16 v[84:87], v[148:151], v[180:183], v[84:87]
	v_mfma_f32_16x16x32_bf16 v[80:83], v[152:155], v[176:179], v[80:83]
	v_mfma_f32_16x16x32_bf16 v[80:83], v[156:159], v[180:183], v[80:83]
	v_mfma_f32_16x16x32_bf16 v[68:71], v[144:147], v[192:195], v[68:71]
	v_mfma_f32_16x16x32_bf16 v[68:71], v[148:151], v[196:199], v[68:71]
	v_mfma_f32_16x16x32_bf16 v[64:67], v[152:155], v[192:195], v[64:67]
	v_mfma_f32_16x16x32_bf16 v[64:67], v[156:159], v[196:199], v[64:67]
	s_setprio 0
	s_barrier
	s_add_i32 s53, s56, s2
	v_lshl_add_u64 v[200:201], s[36:37], 0, v[186:187]
	s_mov_b32 m0, s53
	ds_read_b128 v[160:163], v215 offset:16384
	ds_read_b128 v[164:167], v215 offset:17408
	ds_read_b128 v[168:171], v215 offset:18432
	ds_read_b128 v[172:175], v215 offset:19456
	ds_read_b128 v[176:179], v215 offset:20480
	ds_read_b128 v[180:183], v215 offset:21504
	ds_read_b128 v[192:195], v215 offset:22528
	ds_read_b128 v[196:199], v215 offset:23552
	global_load_lds_dwordx4 v[200:201], off
	s_add_i32 m0, s53, 0x2000
	s_add_u32 s54, s36, 0x208000
	v_lshl_add_u64 v[202:203], s[36:37], 0, v[190:191]
	s_addc_u32 s55, s37, 0
	s_add_i32 s53, s45, s2
	global_load_lds_dwordx4 v[202:203], off
	v_lshl_add_u64 v[204:205], s[54:55], 0, v[186:187]
	s_mov_b32 m0, s53
	s_nop 0
	global_load_lds_dwordx4 v[204:205], off
	v_lshl_add_u64 v[204:205], s[54:55], 0, v[190:191]
	s_add_i32 m0, s53, 0x2000
	s_nop 0
	global_load_lds_dwordx4 v[204:205], off
	v_lshl_add_u64 v[204:205], s[38:39], 0, v[184:185]
	s_mov_b32 m0, s3
	s_nop 0
	global_load_lds_dwordx4 v[204:205], off
	v_lshl_add_u64 v[204:205], s[38:39], 0, v[188:189]
	s_mov_b32 m0, s33
	s_nop 0
	global_load_lds_dwordx4 v[204:205], off
	s_waitcnt vmcnt(8)
	s_waitcnt lgkmcnt(0)
	s_barrier
	s_setprio 1
	s_waitcnt lgkmcnt(0)
	v_mfma_f32_16x16x32_bf16 v[60:63], v[104:107], v[160:163], v[60:63]
	v_mfma_f32_16x16x32_bf16 v[60:63], v[108:111], v[164:167], v[60:63]
	v_mfma_f32_16x16x32_bf16 v[56:59], v[120:123], v[160:163], v[56:59]
	v_mfma_f32_16x16x32_bf16 v[56:59], v[124:127], v[164:167], v[56:59]
	v_mfma_f32_16x16x32_bf16 v[44:47], v[104:107], v[168:171], v[44:47]
	v_mfma_f32_16x16x32_bf16 v[44:47], v[108:111], v[172:175], v[44:47]
	v_mfma_f32_16x16x32_bf16 v[40:43], v[120:123], v[168:171], v[40:43]
	v_mfma_f32_16x16x32_bf16 v[40:43], v[124:127], v[172:175], v[40:43]
	v_mfma_f32_16x16x32_bf16 v[28:31], v[104:107], v[176:179], v[28:31]
	v_mfma_f32_16x16x32_bf16 v[28:31], v[108:111], v[180:183], v[28:31]
	v_mfma_f32_16x16x32_bf16 v[24:27], v[120:123], v[176:179], v[24:27]
	v_mfma_f32_16x16x32_bf16 v[24:27], v[124:127], v[180:183], v[24:27]
	v_mfma_f32_16x16x32_bf16 v[12:15], v[104:107], v[192:195], v[12:15]
	v_mfma_f32_16x16x32_bf16 v[12:15], v[108:111], v[196:199], v[12:15]
	v_mfma_f32_16x16x32_bf16 v[8:11], v[120:123], v[192:195], v[8:11]
	v_mfma_f32_16x16x32_bf16 v[8:11], v[124:127], v[196:199], v[8:11]
	s_setprio 0
	s_setprio 1
	v_mfma_f32_16x16x32_bf16 v[52:55], v[144:147], v[160:163], v[52:55]
	v_mfma_f32_16x16x32_bf16 v[52:55], v[148:151], v[164:167], v[52:55]
	v_mfma_f32_16x16x32_bf16 v[48:51], v[152:155], v[160:163], v[48:51]
	v_mfma_f32_16x16x32_bf16 v[48:51], v[156:159], v[164:167], v[48:51]
	v_mfma_f32_16x16x32_bf16 v[36:39], v[144:147], v[168:171], v[36:39]
	v_mfma_f32_16x16x32_bf16 v[36:39], v[148:151], v[172:175], v[36:39]
	v_mfma_f32_16x16x32_bf16 v[32:35], v[152:155], v[168:171], v[32:35]
	v_mfma_f32_16x16x32_bf16 v[32:35], v[156:159], v[172:175], v[32:35]
	v_mfma_f32_16x16x32_bf16 v[20:23], v[144:147], v[176:179], v[20:23]
	v_mfma_f32_16x16x32_bf16 v[20:23], v[148:151], v[180:183], v[20:23]
	v_mfma_f32_16x16x32_bf16 v[16:19], v[152:155], v[176:179], v[16:19]
	v_mfma_f32_16x16x32_bf16 v[16:19], v[156:159], v[180:183], v[16:19]
	v_mfma_f32_16x16x32_bf16 v[4:7], v[144:147], v[192:195], v[4:7]
	v_mfma_f32_16x16x32_bf16 v[4:7], v[148:151], v[196:199], v[4:7]
	v_mfma_f32_16x16x32_bf16 v[0:3], v[152:155], v[192:195], v[0:3]
	v_mfma_f32_16x16x32_bf16 v[0:3], v[156:159], v[196:199], v[0:3]
	s_setprio 0
	s_barrier
	s_add_i32 s53, 0, 0x18000
	s_add_i32 s54, 0, 0x1c000
	v_add_u32_e32 v124, s53, v211
	v_add_u32_e32 v156, s54, v211
	ds_read_b128 v[104:107], v124
	ds_read_b128 v[108:111], v124 offset:1024
	ds_read_b128 v[120:123], v124 offset:2048
	ds_read_b128 v[124:127], v124 offset:3072
	ds_read_b128 v[144:147], v156
	ds_read_b128 v[148:151], v156 offset:1024
	ds_read_b128 v[152:155], v156 offset:2048
	ds_read_b128 v[156:159], v156 offset:3072
	s_add_u32 s38, s38, 0x10000
	s_addc_u32 s39, s39, 0
	s_mov_b32 m0, s40
	v_lshl_add_u64 v[204:205], s[38:39], 0, v[184:185]
	ds_read_b128 v[160:163], v215 offset:32768
	ds_read_b128 v[164:167], v215 offset:33792
	ds_read_b128 v[168:171], v215 offset:34816
	ds_read_b128 v[172:175], v215 offset:35840
	ds_read_b128 v[176:179], v215 offset:36864
	ds_read_b128 v[180:183], v215 offset:37888
	ds_read_b128 v[192:195], v215 offset:38912
	ds_read_b128 v[196:199], v215 offset:39936
	global_load_lds_dwordx4 v[204:205], off
	v_lshl_add_u64 v[204:205], s[38:39], 0, v[188:189]
	s_mov_b32 m0, s41
	s_nop 0
	global_load_lds_dwordx4 v[204:205], off
	s_waitcnt vmcnt(8)
	s_waitcnt lgkmcnt(0)
	s_barrier
	s_setprio 1
	s_waitcnt lgkmcnt(0)
	v_mfma_f32_16x16x32_bf16 v[140:143], v[104:107], v[160:163], v[140:143]
	v_mfma_f32_16x16x32_bf16 v[140:143], v[108:111], v[164:167], v[140:143]
	v_mfma_f32_16x16x32_bf16 v[136:139], v[120:123], v[160:163], v[136:139]
	v_mfma_f32_16x16x32_bf16 v[136:139], v[124:127], v[164:167], v[136:139]
	v_mfma_f32_16x16x32_bf16 v[116:119], v[104:107], v[168:171], v[116:119]
	v_mfma_f32_16x16x32_bf16 v[116:119], v[108:111], v[172:175], v[116:119]
	v_mfma_f32_16x16x32_bf16 v[112:115], v[120:123], v[168:171], v[112:115]
	v_mfma_f32_16x16x32_bf16 v[112:115], v[124:127], v[172:175], v[112:115]
	v_mfma_f32_16x16x32_bf16 v[92:95], v[104:107], v[176:179], v[92:95]
	v_mfma_f32_16x16x32_bf16 v[92:95], v[108:111], v[180:183], v[92:95]
	v_mfma_f32_16x16x32_bf16 v[88:91], v[120:123], v[176:179], v[88:91]
	v_mfma_f32_16x16x32_bf16 v[88:91], v[124:127], v[180:183], v[88:91]
	v_mfma_f32_16x16x32_bf16 v[76:79], v[104:107], v[192:195], v[76:79]
	v_mfma_f32_16x16x32_bf16 v[76:79], v[108:111], v[196:199], v[76:79]
	v_mfma_f32_16x16x32_bf16 v[72:75], v[120:123], v[192:195], v[72:75]
	v_mfma_f32_16x16x32_bf16 v[72:75], v[124:127], v[196:199], v[72:75]
	s_setprio 0
	s_setprio 1
	v_mfma_f32_16x16x32_bf16 v[132:135], v[144:147], v[160:163], v[132:135]
	v_mfma_f32_16x16x32_bf16 v[132:135], v[148:151], v[164:167], v[132:135]
	v_mfma_f32_16x16x32_bf16 v[128:131], v[152:155], v[160:163], v[128:131]
	v_mfma_f32_16x16x32_bf16 v[128:131], v[156:159], v[164:167], v[128:131]
	v_mfma_f32_16x16x32_bf16 v[100:103], v[144:147], v[168:171], v[100:103]
	v_mfma_f32_16x16x32_bf16 v[100:103], v[148:151], v[172:175], v[100:103]
	v_mfma_f32_16x16x32_bf16 v[96:99], v[152:155], v[168:171], v[96:99]
	v_mfma_f32_16x16x32_bf16 v[96:99], v[156:159], v[172:175], v[96:99]
	v_mfma_f32_16x16x32_bf16 v[84:87], v[144:147], v[176:179], v[84:87]
	v_mfma_f32_16x16x32_bf16 v[84:87], v[148:151], v[180:183], v[84:87]
	v_mfma_f32_16x16x32_bf16 v[80:83], v[152:155], v[176:179], v[80:83]
	v_mfma_f32_16x16x32_bf16 v[80:83], v[156:159], v[180:183], v[80:83]
	v_mfma_f32_16x16x32_bf16 v[68:71], v[144:147], v[192:195], v[68:71]
	v_mfma_f32_16x16x32_bf16 v[68:71], v[148:151], v[196:199], v[68:71]
	v_mfma_f32_16x16x32_bf16 v[64:67], v[152:155], v[192:195], v[64:67]
	v_mfma_f32_16x16x32_bf16 v[64:67], v[156:159], v[196:199], v[64:67]
	s_setprio 0
	s_barrier
	s_add_i32 s38, s53, s2
	v_lshl_add_u64 v[200:201], v[200:201], 0, s[16:17]
	s_mov_b32 m0, s38
	ds_read_b128 v[160:163], v215 offset:49152
	ds_read_b128 v[164:167], v215 offset:50176
	ds_read_b128 v[168:171], v215 offset:51200
	ds_read_b128 v[172:175], v215 offset:52224
	ds_read_b128 v[176:179], v215 offset:53248
	ds_read_b128 v[180:183], v215 offset:54272
	ds_read_b128 v[192:195], v215 offset:55296
	ds_read_b128 v[196:199], v215 offset:56320
	global_load_lds_dwordx4 v[200:201], off
	s_add_i32 m0, s38, 0x2000
	s_add_u32 s36, s36, 0x208080
	v_lshl_add_u64 v[200:201], v[202:203], 0, s[16:17]
	s_addc_u32 s37, s37, 0
	s_add_i32 s38, s54, s2
	global_load_lds_dwordx4 v[200:201], off
	v_lshl_add_u64 v[200:201], s[36:37], 0, v[186:187]
	s_mov_b32 m0, s38
	s_nop 0
	global_load_lds_dwordx4 v[200:201], off
	v_lshl_add_u64 v[200:201], s[36:37], 0, v[190:191]
	s_add_i32 m0, s38, 0x2000
	s_nop 0
	global_load_lds_dwordx4 v[200:201], off
	v_lshl_add_u64 v[200:201], s[30:31], 0, v[184:185]
	s_mov_b32 m0, s43
	s_nop 0
	global_load_lds_dwordx4 v[200:201], off
	v_lshl_add_u64 v[200:201], s[30:31], 0, v[188:189]
	s_mov_b32 m0, s44
	s_nop 0
	global_load_lds_dwordx4 v[200:201], off
	s_waitcnt vmcnt(8)
	s_waitcnt lgkmcnt(0)
	s_barrier
	s_setprio 1
	s_waitcnt lgkmcnt(0)
	v_mfma_f32_16x16x32_bf16 v[60:63], v[104:107], v[160:163], v[60:63]
	v_mfma_f32_16x16x32_bf16 v[60:63], v[108:111], v[164:167], v[60:63]
	v_mfma_f32_16x16x32_bf16 v[56:59], v[120:123], v[160:163], v[56:59]
	v_mfma_f32_16x16x32_bf16 v[56:59], v[124:127], v[164:167], v[56:59]
	v_mfma_f32_16x16x32_bf16 v[44:47], v[104:107], v[168:171], v[44:47]
	v_mfma_f32_16x16x32_bf16 v[44:47], v[108:111], v[172:175], v[44:47]
	v_mfma_f32_16x16x32_bf16 v[40:43], v[120:123], v[168:171], v[40:43]
	v_mfma_f32_16x16x32_bf16 v[40:43], v[124:127], v[172:175], v[40:43]
	v_mfma_f32_16x16x32_bf16 v[28:31], v[104:107], v[176:179], v[28:31]
	v_mfma_f32_16x16x32_bf16 v[28:31], v[108:111], v[180:183], v[28:31]
	v_mfma_f32_16x16x32_bf16 v[24:27], v[120:123], v[176:179], v[24:27]
	v_mfma_f32_16x16x32_bf16 v[24:27], v[124:127], v[180:183], v[24:27]
	v_mfma_f32_16x16x32_bf16 v[12:15], v[104:107], v[192:195], v[12:15]
	v_mfma_f32_16x16x32_bf16 v[12:15], v[108:111], v[196:199], v[12:15]
	v_mfma_f32_16x16x32_bf16 v[8:11], v[120:123], v[192:195], v[8:11]
	v_mfma_f32_16x16x32_bf16 v[8:11], v[124:127], v[196:199], v[8:11]
	s_setprio 0
	s_setprio 1
	v_mfma_f32_16x16x32_bf16 v[52:55], v[144:147], v[160:163], v[52:55]
	v_mfma_f32_16x16x32_bf16 v[52:55], v[148:151], v[164:167], v[52:55]
	v_mfma_f32_16x16x32_bf16 v[48:51], v[152:155], v[160:163], v[48:51]
	v_mfma_f32_16x16x32_bf16 v[48:51], v[156:159], v[164:167], v[48:51]
	v_mfma_f32_16x16x32_bf16 v[36:39], v[144:147], v[168:171], v[36:39]
	v_mfma_f32_16x16x32_bf16 v[36:39], v[148:151], v[172:175], v[36:39]
	v_mfma_f32_16x16x32_bf16 v[32:35], v[152:155], v[168:171], v[32:35]
	v_mfma_f32_16x16x32_bf16 v[32:35], v[156:159], v[172:175], v[32:35]
	v_mfma_f32_16x16x32_bf16 v[20:23], v[144:147], v[176:179], v[20:23]
	v_mfma_f32_16x16x32_bf16 v[20:23], v[148:151], v[180:183], v[20:23]
	v_mfma_f32_16x16x32_bf16 v[16:19], v[152:155], v[176:179], v[16:19]
	v_mfma_f32_16x16x32_bf16 v[16:19], v[156:159], v[180:183], v[16:19]
	v_mfma_f32_16x16x32_bf16 v[4:7], v[144:147], v[192:195], v[4:7]
	v_mfma_f32_16x16x32_bf16 v[4:7], v[148:151], v[196:199], v[4:7]
	v_mfma_f32_16x16x32_bf16 v[0:3], v[152:155], v[192:195], v[0:3]
	v_mfma_f32_16x16x32_bf16 v[0:3], v[156:159], v[196:199], v[0:3]
	s_setprio 0
	s_barrier
	s_add_i32 s51, s51, 2
	s_add_i32 s52, s52, 0x10000
	s_cmpk_gt_u32 s51, 0x7d
	s_mov_b64 s[30:31], s[34:35]
	s_cbranch_scc0 .LBB0_844
	s_and_b64 vcc, exec, s[18:19]
	s_cbranch_vccz .LBB0_847
	s_barrier
